# opt16: row-scale loads issued after the first K tile DMAs at GEMM phase start (overlap round trips, one barrier less)
# baseline (speedup 1.0000x reference)
.LBB0_199:
	s_or_b64 exec, exec, s[0:1]
	s_cmpk_lt_i32 s2, 0x600
	s_cselect_b64 s[4:5], -1, 0
	s_cmpk_gt_i32 s2, 0x5ff
	v_readfirstlane_b32 s8, v128
	s_cbranch_scc0 .LBB0_202
	s_andn2_b64 vcc, exec, s[4:5]
	s_cbranch_vccz .LBB0_203

.LBB0_203:
	v_lshrrev_b32_e32 v2, 1, v128
	v_and_b32_e32 v132, 24, v2
	v_lshrrev_b32_e32 v2, 5, v128
	v_and_b32_e32 v2, 4, v2
	v_bfe_u32 v3, v128, 2, 2
	v_lshlrev_b32_e32 v0, 4, v128
	v_and_b32_e32 v1, 32, v128
	v_bfe_u32 v11, v128, 2, 4
	v_or3_b32 v2, v2, v3, v132
	v_lshrrev_b32_e32 v3, 3, v128
	s_movk_i32 s1, 0x70
	v_bitop3_b32 v9, v0, v1, 48 bitop3:0x6c
	v_and_b32_e32 v10, 64, v128
	v_and_or_b32 v4, v3, s1, v11
	s_movk_i32 s1, 0x60
	v_add_u32_e32 v12, 0x2000, v0
	s_lshr_b32 s5, s8, 6
	s_lshr_b32 s4, s8, 8
	v_or_b32_e32 v1, v9, v10
	v_and_or_b32 v3, v3, s1, v2
	v_lshrrev_b32_e32 v0, 7, v12
	s_movk_i32 s1, 0xf0
	s_lshl_b32 s58, s5, 10
	v_lshl_or_b32 v136, v3, 11, v1
	v_and_or_b32 v3, v0, s1, v11
	s_movk_i32 s1, 0xe0
	s_add_u32 s59, s70, 0x100000
	v_and_or_b32 v0, v0, s1, v2
	s_addc_u32 s62, s71, 0
	s_ashr_i32 s7, s6, 31
	s_ashr_i32 s1, s0, 31
	s_lshl_b64 s[10:11], s[6:7], 19
	s_lshl_b64 s[12:13], s[0:1], 19
	s_add_u32 s52, s59, s12
	s_addc_u32 s53, s62, s13
	s_add_i32 s63, s58, 0
	s_add_i32 m0, s63, 0x10000
	v_lshl_or_b32 v140, v0, 11, v1
	global_load_lds_dwordx4 v136, s[52:53]
	s_add_i32 m0, s63, 0x12000
	s_add_u32 s12, s52, 0x40000
	global_load_lds_dwordx4 v140, s[52:53]
	s_addc_u32 s13, s53, 0
	s_add_i32 m0, s63, 0x14000
	v_lshl_or_b32 v134, v4, 11, v1
	global_load_lds_dwordx4 v136, s[12:13]
	s_add_i32 m0, s63, 0x16000
	s_add_u32 s50, s14, s10
	s_addc_u32 s51, s15, s11
	s_add_i32 s64, s63, 0x2000
	global_load_lds_dwordx4 v140, s[12:13]
	s_mov_b32 m0, s63
	s_add_u32 s10, s50, 0x40000
	v_lshl_or_b32 v138, v3, 11, v1
	global_load_lds_dwordx4 v134, s[50:51]
	s_mov_b32 m0, s64
	s_addc_u32 s11, s51, 0
	s_add_i32 s65, s63, 0x4000
	global_load_lds_dwordx4 v138, s[50:51]
	s_mov_b32 m0, s65
	s_add_i32 s66, s63, 0x6000
	global_load_lds_dwordx4 v134, s[10:11]
	s_mov_b32 m0, s66
	v_mov_b32_e32 v143, 0
	global_load_lds_dwordx4 v138, s[10:11]
	v_and_b32_e32 v114, 0xff, v128
	s_lshr_b32 s98, s91, 2
	v_mov_b32_e32 v115, 0x358637bd
	s_mul_i32 s99, s98, s72
	s_add_i32 s99, s99, s2
	s_cmp_lt_u32 s99, 0x600
	s_cselect_b32 s99, s99, s2
	s_and_b32 s100, s99, 7
	s_mul_i32 s100, s100, 0xc0
	s_lshr_b32 s101, s99, 3
	s_add_i32 s100, s100, s101
	s_mul_hi_u32 s101, s100, 0x2aaaaab
	s_lshl_b32 s101, s101, 3
	s_and_b32 s100, s100, 7
	s_or_b32 s101, s101, s100
	s_lshl_b32 s101, s101, 8
	v_add_u32_e32 v112, s101, v114
	v_lshlrev_b32_e32 v112, 6, v112
	v_mov_b32_e32 v113, 0
	v_lshl_add_u64 v[112:113], s[18:19], 0, v[112:113]
	global_load_dwordx4 v[16:19], v[112:113], off
	global_load_dwordx4 v[20:23], v[112:113], off offset:16
	global_load_dwordx4 v[24:27], v[112:113], off offset:32
	global_load_dwordx4 v[28:31], v[112:113], off offset:48
	s_add_i32 s98, s98, 2
	s_mul_i32 s99, s98, s72
	s_add_i32 s99, s99, s2
	s_cmp_lt_u32 s99, 0x600
	s_cselect_b32 s99, s99, s2
	s_and_b32 s100, s99, 7
	s_mul_i32 s100, s100, 0xc0
	s_lshr_b32 s101, s99, 3
	s_add_i32 s100, s100, s101
	s_mul_hi_u32 s101, s100, 0x2aaaaab
	s_lshl_b32 s101, s101, 3
	s_and_b32 s100, s100, 7
	s_or_b32 s101, s101, s100
	s_lshl_b32 s101, s101, 8
	v_add_u32_e32 v112, s101, v114
	v_lshlrev_b32_e32 v112, 6, v112
	v_mov_b32_e32 v113, 0
	v_lshl_add_u64 v[112:113], s[18:19], 0, v[112:113]
	global_load_dwordx4 v[32:35], v[112:113], off
	global_load_dwordx4 v[36:39], v[112:113], off offset:16
	global_load_dwordx4 v[40:43], v[112:113], off offset:32
	global_load_dwordx4 v[44:47], v[112:113], off offset:48
	s_add_i32 s98, s98, 2
	s_mul_i32 s99, s98, s72
	s_add_i32 s99, s99, s2
	s_cmp_lt_u32 s99, 0x600
	s_cselect_b32 s99, s99, s2
	s_and_b32 s100, s99, 7
	s_mul_i32 s100, s100, 0xc0
	s_lshr_b32 s101, s99, 3
	s_add_i32 s100, s100, s101
	s_mul_hi_u32 s101, s100, 0x2aaaaab
	s_lshl_b32 s101, s101, 3
	s_and_b32 s100, s100, 7
	s_or_b32 s101, s101, s100
	s_lshl_b32 s101, s101, 8
	v_add_u32_e32 v112, s101, v114
	v_lshlrev_b32_e32 v112, 6, v112
	v_mov_b32_e32 v113, 0
	v_lshl_add_u64 v[112:113], s[18:19], 0, v[112:113]
	global_load_dwordx4 v[48:51], v[112:113], off
	global_load_dwordx4 v[52:55], v[112:113], off offset:16
	global_load_dwordx4 v[56:59], v[112:113], off offset:32
	global_load_dwordx4 v[60:63], v[112:113], off offset:48
	s_add_i32 s98, s98, 2
	v_lshlrev_b32_e32 v116, 2, v128
	v_add_u32_e32 v116, 0x20000, v116
	s_waitcnt vmcnt(8)
	v_pk_add_f32 v[118:119], v[18:19], v[22:23]
	v_pk_add_f32 v[120:121], v[16:17], v[20:21]
	v_pk_add_f32 v[122:123], v[26:27], v[30:31]
	v_pk_add_f32 v[124:125], v[24:25], v[28:29]
	v_pk_add_f32 v[118:119], v[118:119], v[122:123]
	v_pk_add_f32 v[120:121], v[120:121], v[124:125]
	v_add_f32_e32 v120, v121, v120
	v_add_f32_e32 v118, v118, v119
	v_add_f32_e32 v118, v120, v118
	v_fmamk_f32 v118, v118, 0x3a800000, v115
	v_rsq_f32_e32 v118, v118
	ds_write_b32 v116, v118
	s_waitcnt vmcnt(4)
	v_pk_add_f32 v[118:119], v[34:35], v[38:39]
	v_pk_add_f32 v[120:121], v[32:33], v[36:37]
	v_pk_add_f32 v[122:123], v[42:43], v[46:47]
	v_pk_add_f32 v[124:125], v[40:41], v[44:45]
	v_pk_add_f32 v[118:119], v[118:119], v[122:123]
	v_pk_add_f32 v[120:121], v[120:121], v[124:125]
	v_add_f32_e32 v120, v121, v120
	v_add_f32_e32 v118, v118, v119
	v_add_f32_e32 v118, v120, v118
	v_fmamk_f32 v118, v118, 0x3a800000, v115
	v_rsq_f32_e32 v118, v118
	ds_write_b32 v116, v118 offset:2048
	s_waitcnt vmcnt(0)
	v_pk_add_f32 v[118:119], v[50:51], v[54:55]
	v_pk_add_f32 v[120:121], v[48:49], v[52:53]
	v_pk_add_f32 v[122:123], v[58:59], v[62:63]
	v_pk_add_f32 v[124:125], v[56:57], v[60:61]
	v_pk_add_f32 v[118:119], v[118:119], v[122:123]
	v_pk_add_f32 v[120:121], v[120:121], v[124:125]
	v_add_f32_e32 v120, v121, v120
	v_add_f32_e32 v118, v118, v119
	v_add_f32_e32 v118, v120, v118
	v_fmamk_f32 v118, v118, 0x3a800000, v115
	v_rsq_f32_e32 v118, v118
	ds_write_b32 v116, v118 offset:4096
	v_mov_b32_e32 v137, v143
	v_mov_b32_e32 v141, v143
	v_mov_b32_e32 v135, v143
	v_mov_b32_e32 v139, v143
	s_cmp_eq_u32 s4, 1
	s_mov_b32 s9, 0
	v_lshl_add_u64 v[6:7], s[52:53], 0, v[136:137]
	v_lshl_add_u64 v[4:5], s[52:53], 0, v[140:141]
	v_lshl_add_u64 v[0:1], s[50:51], 0, v[134:135]
	s_cselect_b64 s[10:11], -1, 0
	s_cmp_lg_u32 s4, 1
	v_lshl_add_u64 v[2:3], s[50:51], 0, v[138:139]
	s_cbranch_scc1 .LBB0_205
	s_barrier
.LBB0_205:
	s_add_u32 s20, s70, 0x13700000
	s_addc_u32 s21, s71, 0
	s_lshl_b32 s5, s5, 5
	s_mov_b64 s[22:23], 0x80
	s_and_b32 s67, s5, 0x60
	s_add_i32 m0, s63, 0x18000
	v_lshl_add_u64 v[6:7], v[6:7], 0, s[22:23]
	s_lshl_b32 s1, s4, 13
	s_lshl_b32 s5, s67, 7
	s_waitcnt vmcnt(2) lgkmcnt(0)
	s_barrier
	global_load_lds_dwordx4 v[6:7], off
	v_lshl_add_u64 v[4:5], v[4:5], 0, s[22:23]
	s_add_i32 m0, s63, 0x1a000
	s_add_i32 s79, s63, 0x8000
	s_add_i32 s81, s63, 0xa000
	global_load_lds_dwordx4 v[4:5], off
	v_lshl_add_u64 v[0:1], v[0:1], 0, s[22:23]
	s_mov_b32 m0, s79
	s_add_u32 s12, s52, 0x40080
	global_load_lds_dwordx4 v[0:1], off
	v_lshl_add_u64 v[0:1], v[2:3], 0, s[22:23]
	s_mov_b32 m0, s81
	s_addc_u32 s13, s53, 0
	global_load_lds_dwordx4 v[0:1], off
	s_add_i32 m0, s63, 0x1c000
	v_lshl_add_u64 v[0:1], s[12:13], 0, v[136:137]
	global_load_lds_dwordx4 v[0:1], off
	v_lshl_add_u64 v[0:1], s[12:13], 0, v[140:141]
	s_add_i32 m0, s63, 0x1e000
	s_cmpk_lt_u32 s8, 0x100
	global_load_lds_dwordx4 v[0:1], off
	v_and_b32_e32 v0, 15, v128
	v_lshlrev_b32_e32 v1, 1, v132
	v_lshl_or_b32 v131, s4, 6, v0
	v_lshl_or_b32 v2, v0, 6, v1
	v_lshlrev_b32_e32 v0, 2, v0
	v_and_b32_e32 v3, 32, v0
	v_bitop3_b32 v2, v2, s1, v3 bitop3:0xde
	v_lshlrev_b32_e32 v3, 6, v128
	s_movk_i32 s1, 0x3c0
	v_and_or_b32 v1, v3, s1, v1
	s_cselect_b64 s[26:27], -1, 0
	s_lshl_b32 s1, s4, 8
	s_add_i32 s1, s1, 0
	s_add_i32 s1, s1, 0x20000
	v_and_b32_e32 v3, 32, v8
	v_add_u32_e32 v156, s1, v0
	v_lshlrev_b32_e32 v0, 8, v128
	v_bitop3_b32 v133, s5, v1, v3 bitop3:0xf6
	v_and_b32_e32 v0, 0x38000, v0
	v_lshlrev_b32_e32 v1, 11, v11
	v_or3_b32 v0, v9, v0, v1
	v_add_u32_e32 v144, v0, v10
	v_lshlrev_b32_e32 v0, 4, v12
	s_waitcnt vmcnt(6)
	v_and_b32_e32 v0, 0x78000, v0
	v_or3_b32 v0, v9, v0, v1
	s_add_i32 s82, 0, 0x10000
	s_add_i32 s83, 0, 0x14000
	v_mov_b32_e32 v145, v143
	v_add_u32_e32 v146, v0, v10
	v_mov_b32_e32 v147, v143
	v_mov_b64_e32 v[148:149], 0x600
	v_mov_b64_e32 v[150:151], 0x5ff
	s_movk_i32 s77, 0xc1
	v_add_u32_e32 v157, s82, v133
	v_add_u32_e32 v158, s83, v133
	v_add_u32_e32 v159, 0, v2
	s_mov_b32 s1, 0
	s_mov_b32 s84, 0
	s_barrier
	s_branch .LBB0_208

.LBB0_467:
	s_or_b64 exec, exec, s[0:1]
	s_cmpk_gt_i32 s2, 0xaff
	v_readfirstlane_b32 s5, v128
	s_cbranch_scc1 .LBB0_483
	v_lshrrev_b32_e32 v0, 5, v128
	v_lshrrev_b32_e32 v2, 1, v128
	v_and_b32_e32 v0, 4, v0
	v_bfe_u32 v1, v128, 2, 2
	v_and_b32_e32 v12, 24, v2
	v_or3_b32 v0, v0, v1, v12
	v_lshlrev_b32_e32 v1, 4, v128
	v_add_u32_e32 v9, 0x2000, v1
	v_lshrrev_b32_e32 v2, 7, v9
	s_movk_i32 s0, 0xe0
	v_and_b32_e32 v4, 32, v128
	v_and_or_b32 v3, v2, s0, v0
	v_bitop3_b32 v10, v1, v4, 48 bitop3:0x6c
	v_and_b32_e32 v11, 64, v128
	v_bfe_u32 v13, v128, 2, 4
	s_movk_i32 s0, 0xf0
	s_lshr_b32 s6, s5, 6
	v_or_b32_e32 v1, v10, v11
	v_and_or_b32 v2, v2, s0, v13
	s_lshr_b32 s10, s5, 8
	s_lshl_b32 s54, s6, 10
	v_lshl_or_b32 v134, v2, 11, v1
	v_lshrrev_b32_e32 v2, 3, v128
	s_movk_i32 s0, 0x60
	s_add_u32 s55, s70, 0x900000
	v_and_or_b32 v0, v2, s0, v0
	s_movk_i32 s0, 0x70
	s_addc_u32 s56, s71, 0
	v_lshl_or_b32 v136, v0, 11, v1
	v_and_or_b32 v0, v2, s0, v13
	s_lshr_b32 s0, s3, 29
	s_add_i32 s0, s2, s0
	s_ashr_i32 s1, s0, 3
	s_and_b32 s0, s0, -8
	s_sub_i32 s0, s2, s0
	s_cmp_lt_i32 s0, 0
	s_movk_i32 s57, 0x161
	s_cselect_b32 s4, s57, 0x160
	s_mul_i32 s0, s0, s4
	s_add_i32 s0, s0, s1
	s_mul_hi_i32 s1, s0, 0x2e8ba2e9
	s_lshr_b32 s4, s1, 31
	s_ashr_i32 s1, s1, 5
	s_add_i32 s1, s1, s4
	s_lshl_b32 s7, s1, 3
	s_mulk_i32 s1, 0xb0
	s_sub_i32 s0, s0, s1
	s_bfe_u32 s1, s0, 0x3001c
	s_add_i32 s1, s0, s1
	s_sext_i32_i16 s4, s1
	s_and_b32 s1, s1, 0xfff8
	s_sub_i32 s0, s0, s1
	s_sext_i32_i16 s0, s0
	s_lshr_b32 s4, s4, 3
	s_add_i32 s40, s7, s0
	s_ashr_i32 s41, s40, 31
	s_bfe_i64 s[8:9], s[4:5], 0x100000
	s_lshl_b64 s[0:1], s[40:41], 19
	s_lshl_b64 s[8:9], s[8:9], 19
	s_add_u32 s48, s55, s8
	s_addc_u32 s49, s56, s9
	s_add_i32 s41, s54, 0
	s_add_i32 m0, s41, 0x10000
	v_lshl_or_b32 v132, v3, 11, v1
	global_load_lds_dwordx4 v136, s[48:49]
	s_add_i32 m0, s41, 0x12000
	s_add_u32 s8, s48, 0x40000
	global_load_lds_dwordx4 v132, s[48:49]
	s_addc_u32 s9, s49, 0
	s_add_i32 m0, s41, 0x14000
	v_lshl_or_b32 v138, v0, 11, v1
	global_load_lds_dwordx4 v136, s[8:9]
	s_add_i32 m0, s41, 0x16000
	s_add_u32 s42, s14, s0
	s_addc_u32 s43, s15, s1
	s_add_i32 s58, s41, 0x2000
	global_load_lds_dwordx4 v132, s[8:9]
	s_mov_b32 m0, s41
	s_add_u32 s0, s42, 0x40000
	global_load_lds_dwordx4 v138, s[42:43]
	s_mov_b32 m0, s58
	s_addc_u32 s1, s43, 0
	s_add_i32 s59, s41, 0x4000
	global_load_lds_dwordx4 v134, s[42:43]
	s_mov_b32 m0, s59
	s_add_i32 s62, s41, 0x6000
	global_load_lds_dwordx4 v138, s[0:1]
	s_mov_b32 m0, s62
	v_mov_b32_e32 v137, 0
	global_load_lds_dwordx4 v134, s[0:1]
	v_and_b32_e32 v114, 0xff, v128
	s_lshr_b32 s98, s91, 2
	v_mov_b32_e32 v115, 0x358637bd
	s_mul_i32 s99, s98, s72
	s_add_i32 s99, s99, s2
	s_cmp_lt_u32 s99, 0xb00
	s_cselect_b32 s99, s99, s2
	s_and_b32 s100, s99, 7
	s_mul_i32 s100, s100, 0x160
	s_lshr_b32 s101, s99, 3
	s_add_i32 s100, s100, s101
	s_mul_hi_u32 s101, s100, 0x1745d18
	s_lshl_b32 s101, s101, 3
	s_and_b32 s100, s100, 7
	s_or_b32 s101, s101, s100
	s_lshl_b32 s101, s101, 8
	v_add_u32_e32 v112, s101, v114
	v_lshlrev_b32_e32 v112, 6, v112
	v_mov_b32_e32 v113, 0
	v_lshl_add_u64 v[112:113], s[18:19], 0, v[112:113]
	global_load_dwordx4 v[16:19], v[112:113], off
	global_load_dwordx4 v[20:23], v[112:113], off offset:16
	global_load_dwordx4 v[24:27], v[112:113], off offset:32
	global_load_dwordx4 v[28:31], v[112:113], off offset:48
	s_add_i32 s98, s98, 2
	s_mul_i32 s99, s98, s72
	s_add_i32 s99, s99, s2
	s_cmp_lt_u32 s99, 0xb00
	s_cselect_b32 s99, s99, s2
	s_and_b32 s100, s99, 7
	s_mul_i32 s100, s100, 0x160
	s_lshr_b32 s101, s99, 3
	s_add_i32 s100, s100, s101
	s_mul_hi_u32 s101, s100, 0x1745d18
	s_lshl_b32 s101, s101, 3
	s_and_b32 s100, s100, 7
	s_or_b32 s101, s101, s100
	s_lshl_b32 s101, s101, 8
	v_add_u32_e32 v112, s101, v114
	v_lshlrev_b32_e32 v112, 6, v112
	v_mov_b32_e32 v113, 0
	v_lshl_add_u64 v[112:113], s[18:19], 0, v[112:113]
	global_load_dwordx4 v[32:35], v[112:113], off
	global_load_dwordx4 v[36:39], v[112:113], off offset:16
	global_load_dwordx4 v[40:43], v[112:113], off offset:32
	global_load_dwordx4 v[44:47], v[112:113], off offset:48
	s_add_i32 s98, s98, 2
	s_mul_i32 s99, s98, s72
	s_add_i32 s99, s99, s2
	s_cmp_lt_u32 s99, 0xb00
	s_cselect_b32 s99, s99, s2
	s_and_b32 s100, s99, 7
	s_mul_i32 s100, s100, 0x160
	s_lshr_b32 s101, s99, 3
	s_add_i32 s100, s100, s101
	s_mul_hi_u32 s101, s100, 0x1745d18
	s_lshl_b32 s101, s101, 3
	s_and_b32 s100, s100, 7
	s_or_b32 s101, s101, s100
	s_lshl_b32 s101, s101, 8
	v_add_u32_e32 v112, s101, v114
	v_lshlrev_b32_e32 v112, 6, v112
	v_mov_b32_e32 v113, 0
	v_lshl_add_u64 v[112:113], s[18:19], 0, v[112:113]
	global_load_dwordx4 v[48:51], v[112:113], off
	global_load_dwordx4 v[52:55], v[112:113], off offset:16
	global_load_dwordx4 v[56:59], v[112:113], off offset:32
	global_load_dwordx4 v[60:63], v[112:113], off offset:48
	s_add_i32 s98, s98, 2
	s_mul_i32 s99, s98, s72
	s_add_i32 s99, s99, s2
	s_cmp_lt_u32 s99, 0xb00
	s_cselect_b32 s99, s99, s2
	s_and_b32 s100, s99, 7
	s_mul_i32 s100, s100, 0x160
	s_lshr_b32 s101, s99, 3
	s_add_i32 s100, s100, s101
	s_mul_hi_u32 s101, s100, 0x1745d18
	s_lshl_b32 s101, s101, 3
	s_and_b32 s100, s100, 7
	s_or_b32 s101, s101, s100
	s_lshl_b32 s101, s101, 8
	v_add_u32_e32 v112, s101, v114
	v_lshlrev_b32_e32 v112, 6, v112
	v_mov_b32_e32 v113, 0
	v_lshl_add_u64 v[112:113], s[18:19], 0, v[112:113]
	global_load_dwordx4 v[64:67], v[112:113], off
	global_load_dwordx4 v[68:71], v[112:113], off offset:16
	global_load_dwordx4 v[72:75], v[112:113], off offset:32
	global_load_dwordx4 v[76:79], v[112:113], off offset:48
	s_add_i32 s98, s98, 2
	s_mul_i32 s99, s98, s72
	s_add_i32 s99, s99, s2
	s_cmp_lt_u32 s99, 0xb00
	s_cselect_b32 s99, s99, s2
	s_and_b32 s100, s99, 7
	s_mul_i32 s100, s100, 0x160
	s_lshr_b32 s101, s99, 3
	s_add_i32 s100, s100, s101
	s_mul_hi_u32 s101, s100, 0x1745d18
	s_lshl_b32 s101, s101, 3
	s_and_b32 s100, s100, 7
	s_or_b32 s101, s101, s100
	s_lshl_b32 s101, s101, 8
	v_add_u32_e32 v112, s101, v114
	v_lshlrev_b32_e32 v112, 6, v112
	v_mov_b32_e32 v113, 0
	v_lshl_add_u64 v[112:113], s[18:19], 0, v[112:113]
	global_load_dwordx4 v[80:83], v[112:113], off
	global_load_dwordx4 v[84:87], v[112:113], off offset:16
	global_load_dwordx4 v[88:91], v[112:113], off offset:32
	global_load_dwordx4 v[92:95], v[112:113], off offset:48
	s_add_i32 s98, s98, 2
	s_mul_i32 s99, s98, s72
	s_add_i32 s99, s99, s2
	s_cmp_lt_u32 s99, 0xb00
	s_cselect_b32 s99, s99, s2
	s_and_b32 s100, s99, 7
	s_mul_i32 s100, s100, 0x160
	s_lshr_b32 s101, s99, 3
	s_add_i32 s100, s100, s101
	s_mul_hi_u32 s101, s100, 0x1745d18
	s_lshl_b32 s101, s101, 3
	s_and_b32 s100, s100, 7
	s_or_b32 s101, s101, s100
	s_lshl_b32 s101, s101, 8
	v_add_u32_e32 v112, s101, v114
	v_lshlrev_b32_e32 v112, 6, v112
	v_mov_b32_e32 v113, 0
	v_lshl_add_u64 v[112:113], s[18:19], 0, v[112:113]
	global_load_dwordx4 v[96:99], v[112:113], off
	global_load_dwordx4 v[100:103], v[112:113], off offset:16
	global_load_dwordx4 v[104:107], v[112:113], off offset:32
	global_load_dwordx4 v[108:111], v[112:113], off offset:48
	s_add_i32 s98, s98, 2
	v_lshlrev_b32_e32 v116, 2, v128
	v_add_u32_e32 v116, 0x20000, v116
	s_waitcnt vmcnt(20)
	v_pk_add_f32 v[118:119], v[18:19], v[22:23]
	v_pk_add_f32 v[120:121], v[16:17], v[20:21]
	v_pk_add_f32 v[122:123], v[26:27], v[30:31]
	v_pk_add_f32 v[124:125], v[24:25], v[28:29]
	v_pk_add_f32 v[118:119], v[118:119], v[122:123]
	v_pk_add_f32 v[120:121], v[120:121], v[124:125]
	v_add_f32_e32 v120, v121, v120
	v_add_f32_e32 v118, v118, v119
	v_add_f32_e32 v118, v120, v118
	v_fmamk_f32 v118, v118, 0x3a800000, v115
	v_rsq_f32_e32 v118, v118
	ds_write_b32 v116, v118
	s_waitcnt vmcnt(16)
	v_pk_add_f32 v[118:119], v[34:35], v[38:39]
	v_pk_add_f32 v[120:121], v[32:33], v[36:37]
	v_pk_add_f32 v[122:123], v[42:43], v[46:47]
	v_pk_add_f32 v[124:125], v[40:41], v[44:45]
	v_pk_add_f32 v[118:119], v[118:119], v[122:123]
	v_pk_add_f32 v[120:121], v[120:121], v[124:125]
	v_add_f32_e32 v120, v121, v120
	v_add_f32_e32 v118, v118, v119
	v_add_f32_e32 v118, v120, v118
	v_fmamk_f32 v118, v118, 0x3a800000, v115
	v_rsq_f32_e32 v118, v118
	ds_write_b32 v116, v118 offset:2048
	s_waitcnt vmcnt(12)
	v_pk_add_f32 v[118:119], v[50:51], v[54:55]
	v_pk_add_f32 v[120:121], v[48:49], v[52:53]
	v_pk_add_f32 v[122:123], v[58:59], v[62:63]
	v_pk_add_f32 v[124:125], v[56:57], v[60:61]
	v_pk_add_f32 v[118:119], v[118:119], v[122:123]
	v_pk_add_f32 v[120:121], v[120:121], v[124:125]
	v_add_f32_e32 v120, v121, v120
	v_add_f32_e32 v118, v118, v119
	v_add_f32_e32 v118, v120, v118
	v_fmamk_f32 v118, v118, 0x3a800000, v115
	v_rsq_f32_e32 v118, v118
	ds_write_b32 v116, v118 offset:4096
	s_waitcnt vmcnt(8)
	v_pk_add_f32 v[118:119], v[66:67], v[70:71]
	v_pk_add_f32 v[120:121], v[64:65], v[68:69]
	v_pk_add_f32 v[122:123], v[74:75], v[78:79]
	v_pk_add_f32 v[124:125], v[72:73], v[76:77]
	v_pk_add_f32 v[118:119], v[118:119], v[122:123]
	v_pk_add_f32 v[120:121], v[120:121], v[124:125]
	v_add_f32_e32 v120, v121, v120
	v_add_f32_e32 v118, v118, v119
	v_add_f32_e32 v118, v120, v118
	v_fmamk_f32 v118, v118, 0x3a800000, v115
	v_rsq_f32_e32 v118, v118
	ds_write_b32 v116, v118 offset:6144
	s_waitcnt vmcnt(4)
	v_pk_add_f32 v[118:119], v[82:83], v[86:87]
	v_pk_add_f32 v[120:121], v[80:81], v[84:85]
	v_pk_add_f32 v[122:123], v[90:91], v[94:95]
	v_pk_add_f32 v[124:125], v[88:89], v[92:93]
	v_pk_add_f32 v[118:119], v[118:119], v[122:123]
	v_pk_add_f32 v[120:121], v[120:121], v[124:125]
	v_add_f32_e32 v120, v121, v120
	v_add_f32_e32 v118, v118, v119
	v_add_f32_e32 v118, v120, v118
	v_fmamk_f32 v118, v118, 0x3a800000, v115
	v_rsq_f32_e32 v118, v118
	ds_write_b32 v116, v118 offset:8192
	s_waitcnt vmcnt(0)
	v_pk_add_f32 v[118:119], v[98:99], v[102:103]
	v_pk_add_f32 v[120:121], v[96:97], v[100:101]
	v_pk_add_f32 v[122:123], v[106:107], v[110:111]
	v_pk_add_f32 v[124:125], v[104:105], v[108:109]
	v_pk_add_f32 v[118:119], v[118:119], v[122:123]
	v_pk_add_f32 v[120:121], v[120:121], v[124:125]
	v_add_f32_e32 v120, v121, v120
	v_add_f32_e32 v118, v118, v119
	v_add_f32_e32 v118, v120, v118
	v_fmamk_f32 v118, v118, 0x3a800000, v115
	v_rsq_f32_e32 v118, v118
	ds_write_b32 v116, v118 offset:10240
	v_mov_b32_e32 v133, v137
	v_mov_b32_e32 v139, v137
	v_mov_b32_e32 v135, v137
	s_cmp_eq_u32 s10, 1
	s_mov_b32 s12, 0
	v_lshl_add_u64 v[6:7], s[48:49], 0, v[136:137]
	v_lshl_add_u64 v[4:5], s[48:49], 0, v[132:133]
	v_lshl_add_u64 v[0:1], s[42:43], 0, v[138:139]
	s_cselect_b64 s[0:1], -1, 0
	s_cmp_lg_u32 s10, 1
	v_lshl_add_u64 v[2:3], s[42:43], 0, v[134:135]
	s_cbranch_scc1 .LBB0_470
	s_barrier
.LBB0_470:
	s_lshl_b32 s6, s6, 5
	s_and_b32 s22, s6, 0x60
	s_mov_b64 s[6:7], 0x80
	s_add_i32 m0, s41, 0x18000
	v_lshl_add_u64 v[6:7], v[6:7], 0, s[6:7]
	s_lshl_b32 s11, s10, 13
	s_lshl_b32 s23, s22, 7
	s_waitcnt vmcnt(2) lgkmcnt(0)
	s_barrier
	global_load_lds_dwordx4 v[6:7], off
	v_lshl_add_u64 v[4:5], v[4:5], 0, s[6:7]
	s_add_i32 m0, s41, 0x1a000
	s_add_i32 s63, s41, 0x8000
	s_add_i32 s64, s41, 0xa000
	global_load_lds_dwordx4 v[4:5], off
	v_lshl_add_u64 v[0:1], v[0:1], 0, s[6:7]
	s_mov_b32 m0, s63
	s_add_u32 s8, s48, 0x40080
	global_load_lds_dwordx4 v[0:1], off
	v_lshl_add_u64 v[0:1], v[2:3], 0, s[6:7]
	s_mov_b32 m0, s64
	s_addc_u32 s9, s49, 0
	global_load_lds_dwordx4 v[0:1], off
	s_add_i32 m0, s41, 0x1c000
	v_lshl_add_u64 v[0:1], s[8:9], 0, v[136:137]
	global_load_lds_dwordx4 v[0:1], off
	v_lshl_add_u64 v[0:1], s[8:9], 0, v[132:133]
	s_add_i32 m0, s41, 0x1e000
	s_sext_i32_i16 s13, s4
	global_load_lds_dwordx4 v[0:1], off
	v_and_b32_e32 v0, 15, v128
	v_lshlrev_b32_e32 v1, 1, v12
	v_lshl_or_b32 v131, s10, 6, v0
	v_lshl_or_b32 v2, v0, 6, v1
	v_lshlrev_b32_e32 v0, 2, v0
	v_and_b32_e32 v3, 32, v0
	v_bitop3_b32 v2, v2, s11, v3 bitop3:0xde
	v_lshlrev_b32_e32 v3, 6, v128
	s_movk_i32 s4, 0x3c0
	s_cmpk_lt_u32 s5, 0x100
	v_and_or_b32 v1, v3, s4, v1
	s_cselect_b64 s[8:9], -1, 0
	s_lshl_b32 s4, s10, 8
	s_add_i32 s4, s4, 0
	s_add_i32 s4, s4, 0x20000
	v_and_b32_e32 v3, 32, v8
	v_add_u32_e32 v153, s4, v0
	v_lshlrev_b32_e32 v0, 8, v128
	v_bitop3_b32 v152, s23, v1, v3 bitop3:0xf6
	v_and_b32_e32 v0, 0x38000, v0
	v_lshlrev_b32_e32 v1, 11, v13
	v_or3_b32 v0, v10, v0, v1
	v_add_u32_e32 v140, v0, v11
	v_lshlrev_b32_e32 v0, 4, v9
	s_waitcnt vmcnt(6)
	v_and_b32_e32 v0, 0x78000, v0
	v_or3_b32 v0, v10, v0, v1
	s_add_i32 s65, 0, 0x10000
	s_add_i32 s66, 0, 0x14000
	v_or_b32_e32 v154, s22, v12
	v_mov_b32_e32 v141, v137
	v_add_u32_e32 v142, v0, v11
	v_mov_b32_e32 v143, v137
	v_mov_b64_e32 v[144:145], 0xb00
	v_mov_b64_e32 v[146:147], 0xaff
	v_add_u32_e32 v155, s65, v152
	v_add_u32_e32 v157, s66, v152
	v_add_u32_e32 v158, 0, v2
	s_movk_i32 s67, 0x1600
	s_mov_b32 s77, 0
	s_barrier
	s_branch .LBB0_473

.LBB0_643:
	s_or_b64 exec, exec, s[0:1]
	s_cmpk_lt_i32 s2, 0x600
	s_cselect_b64 s[4:5], -1, 0
	s_cmpk_gt_i32 s2, 0x5ff
	v_readfirstlane_b32 s6, v128
	s_cbranch_scc0 .LBB0_646
	s_andn2_b64 vcc, exec, s[4:5]
	s_cbranch_vccz .LBB0_647

.LBB0_647:
	v_lshrrev_b32_e32 v2, 1, v128
	v_lshrrev_b32_e32 v3, 5, v128
	v_and_b32_e32 v2, 24, v2
	v_and_b32_e32 v3, 4, v3
	v_bfe_u32 v4, v128, 2, 2
	v_lshlrev_b32_e32 v0, 4, v128
	v_and_b32_e32 v1, 32, v128
	v_bfe_u32 v11, v128, 2, 4
	v_or3_b32 v2, v3, v4, v2
	v_lshrrev_b32_e32 v3, 3, v128
	s_movk_i32 s1, 0x70
	s_lshr_b32 s4, s6, 6
	v_bitop3_b32 v9, v0, v1, 48 bitop3:0x6c
	v_and_b32_e32 v10, 64, v128
	v_and_or_b32 v4, v3, s1, v11
	s_movk_i32 s1, 0x60
	v_add_u32_e32 v12, 0x2000, v0
	v_or_b32_e32 v1, v9, v10
	v_and_or_b32 v3, v3, s1, v2
	v_lshrrev_b32_e32 v0, 7, v12
	s_movk_i32 s1, 0xf0
	s_lshr_b32 s7, s6, 8
	s_lshl_b32 s62, s4, 10
	v_lshl_or_b32 v134, v3, 11, v1
	v_and_or_b32 v3, v0, s1, v11
	s_movk_i32 s1, 0xe0
	s_add_u32 s63, s70, 0x1980000
	v_and_or_b32 v0, v0, s1, v2
	s_addc_u32 s64, s71, 0
	s_ashr_i32 s9, s8, 31
	s_ashr_i32 s1, s0, 31
	s_lshl_b64 s[10:11], s[8:9], 19
	s_lshl_b64 s[12:13], s[0:1], 19
	s_add_u32 s54, s63, s12
	s_addc_u32 s55, s64, s13
	s_add_i32 s65, s62, 0
	s_add_i32 m0, s65, 0x10000
	v_lshl_or_b32 v138, v0, 11, v1
	global_load_lds_dwordx4 v134, s[54:55]
	s_add_i32 m0, s65, 0x12000
	s_add_u32 s12, s54, 0x40000
	global_load_lds_dwordx4 v138, s[54:55]
	s_addc_u32 s13, s55, 0
	s_add_i32 m0, s65, 0x14000
	v_lshl_or_b32 v132, v4, 11, v1
	global_load_lds_dwordx4 v134, s[12:13]
	s_add_i32 m0, s65, 0x16000
	s_add_u32 s52, s14, s10
	s_addc_u32 s53, s15, s11
	s_add_i32 s66, s65, 0x2000
	global_load_lds_dwordx4 v138, s[12:13]
	s_mov_b32 m0, s65
	s_add_u32 s10, s52, 0x40000
	v_lshl_or_b32 v136, v3, 11, v1
	global_load_lds_dwordx4 v132, s[52:53]
	s_mov_b32 m0, s66
	s_addc_u32 s11, s53, 0
	s_add_i32 s67, s65, 0x4000
	global_load_lds_dwordx4 v136, s[52:53]
	s_mov_b32 m0, s67
	s_add_i32 s79, s65, 0x6000
	global_load_lds_dwordx4 v132, s[10:11]
	s_mov_b32 m0, s79
	v_writelane_b32 v238, s94, 4
	global_load_lds_dwordx4 v136, s[10:11]
	v_and_b32_e32 v114, 0xff, v128
	s_lshr_b32 s98, s91, 2
	v_mov_b32_e32 v115, 0x358637bd
	s_mul_i32 s99, s98, s72
	s_add_i32 s99, s99, s2
	s_cmp_lt_u32 s99, 0x600
	s_cselect_b32 s99, s99, s2
	s_and_b32 s100, s99, 7
	s_mul_i32 s100, s100, 0xc0
	s_lshr_b32 s101, s99, 3
	s_add_i32 s100, s100, s101
	s_mul_hi_u32 s101, s100, 0x2aaaaab
	s_lshl_b32 s101, s101, 3
	s_and_b32 s100, s100, 7
	s_or_b32 s101, s101, s100
	s_lshl_b32 s101, s101, 8
	v_add_u32_e32 v112, s101, v114
	v_lshlrev_b32_e32 v112, 6, v112
	v_mov_b32_e32 v113, 0
	v_lshl_add_u64 v[112:113], s[18:19], 0, v[112:113]
	global_load_dwordx4 v[16:19], v[112:113], off
	global_load_dwordx4 v[20:23], v[112:113], off offset:16
	global_load_dwordx4 v[24:27], v[112:113], off offset:32
	global_load_dwordx4 v[28:31], v[112:113], off offset:48
	s_add_i32 s98, s98, 2
	s_mul_i32 s99, s98, s72
	s_add_i32 s99, s99, s2
	s_cmp_lt_u32 s99, 0x600
	s_cselect_b32 s99, s99, s2
	s_and_b32 s100, s99, 7
	s_mul_i32 s100, s100, 0xc0
	s_lshr_b32 s101, s99, 3
	s_add_i32 s100, s100, s101
	s_mul_hi_u32 s101, s100, 0x2aaaaab
	s_lshl_b32 s101, s101, 3
	s_and_b32 s100, s100, 7
	s_or_b32 s101, s101, s100
	s_lshl_b32 s101, s101, 8
	v_add_u32_e32 v112, s101, v114
	v_lshlrev_b32_e32 v112, 6, v112
	v_mov_b32_e32 v113, 0
	v_lshl_add_u64 v[112:113], s[18:19], 0, v[112:113]
	global_load_dwordx4 v[32:35], v[112:113], off
	global_load_dwordx4 v[36:39], v[112:113], off offset:16
	global_load_dwordx4 v[40:43], v[112:113], off offset:32
	global_load_dwordx4 v[44:47], v[112:113], off offset:48
	s_add_i32 s98, s98, 2
	s_mul_i32 s99, s98, s72
	s_add_i32 s99, s99, s2
	s_cmp_lt_u32 s99, 0x600
	s_cselect_b32 s99, s99, s2
	s_and_b32 s100, s99, 7
	s_mul_i32 s100, s100, 0xc0
	s_lshr_b32 s101, s99, 3
	s_add_i32 s100, s100, s101
	s_mul_hi_u32 s101, s100, 0x2aaaaab
	s_lshl_b32 s101, s101, 3
	s_and_b32 s100, s100, 7
	s_or_b32 s101, s101, s100
	s_lshl_b32 s101, s101, 8
	v_add_u32_e32 v112, s101, v114
	v_lshlrev_b32_e32 v112, 6, v112
	v_mov_b32_e32 v113, 0
	v_lshl_add_u64 v[112:113], s[18:19], 0, v[112:113]
	global_load_dwordx4 v[48:51], v[112:113], off
	global_load_dwordx4 v[52:55], v[112:113], off offset:16
	global_load_dwordx4 v[56:59], v[112:113], off offset:32
	global_load_dwordx4 v[60:63], v[112:113], off offset:48
	s_add_i32 s98, s98, 2
	v_lshlrev_b32_e32 v116, 2, v128
	v_add_u32_e32 v116, 0x20000, v116
	s_waitcnt vmcnt(8)
	v_pk_add_f32 v[118:119], v[18:19], v[22:23]
	v_pk_add_f32 v[120:121], v[16:17], v[20:21]
	v_pk_add_f32 v[122:123], v[26:27], v[30:31]
	v_pk_add_f32 v[124:125], v[24:25], v[28:29]
	v_pk_add_f32 v[118:119], v[118:119], v[122:123]
	v_pk_add_f32 v[120:121], v[120:121], v[124:125]
	v_add_f32_e32 v120, v121, v120
	v_add_f32_e32 v118, v118, v119
	v_add_f32_e32 v118, v120, v118
	v_fmamk_f32 v118, v118, 0x3a800000, v115
	v_rsq_f32_e32 v118, v118
	ds_write_b32 v116, v118
	s_waitcnt vmcnt(4)
	v_pk_add_f32 v[118:119], v[34:35], v[38:39]
	v_pk_add_f32 v[120:121], v[32:33], v[36:37]
	v_pk_add_f32 v[122:123], v[42:43], v[46:47]
	v_pk_add_f32 v[124:125], v[40:41], v[44:45]
	v_pk_add_f32 v[118:119], v[118:119], v[122:123]
	v_pk_add_f32 v[120:121], v[120:121], v[124:125]
	v_add_f32_e32 v120, v121, v120
	v_add_f32_e32 v118, v118, v119
	v_add_f32_e32 v118, v120, v118
	v_fmamk_f32 v118, v118, 0x3a800000, v115
	v_rsq_f32_e32 v118, v118
	ds_write_b32 v116, v118 offset:2048
	s_waitcnt vmcnt(0)
	v_pk_add_f32 v[118:119], v[50:51], v[54:55]
	v_pk_add_f32 v[120:121], v[48:49], v[52:53]
	v_pk_add_f32 v[122:123], v[58:59], v[62:63]
	v_pk_add_f32 v[124:125], v[56:57], v[60:61]
	v_pk_add_f32 v[118:119], v[118:119], v[122:123]
	v_pk_add_f32 v[120:121], v[120:121], v[124:125]
	v_add_f32_e32 v120, v121, v120
	v_add_f32_e32 v118, v118, v119
	v_add_f32_e32 v118, v120, v118
	v_fmamk_f32 v118, v118, 0x3a800000, v115
	v_rsq_f32_e32 v118, v118
	ds_write_b32 v116, v118 offset:4096
	v_mov_b32_e32 v135, 0
	v_writelane_b32 v238, s95, 5
	v_mov_b32_e32 v139, v135
	v_mov_b32_e32 v133, v135
	v_mov_b32_e32 v137, v135
	s_cmp_eq_u32 s7, 1
	v_writelane_b32 v238, s92, 6
	s_mov_b32 s11, 0
	v_lshl_add_u64 v[6:7], s[54:55], 0, v[134:135]
	v_lshl_add_u64 v[4:5], s[54:55], 0, v[138:139]
	v_lshl_add_u64 v[0:1], s[52:53], 0, v[132:133]
	s_cselect_b64 s[22:23], -1, 0
	s_cmp_lg_u32 s7, 1
	v_lshl_add_u64 v[2:3], s[52:53], 0, v[136:137]
	v_writelane_b32 v238, s93, 7
	s_cbranch_scc1 .LBB0_649
	s_barrier
.LBB0_649:
	s_add_u32 s81, s70, 0x1f900000
	s_mov_b64 s[26:27], 0x80
	s_addc_u32 s82, s71, 0
	s_and_b32 s1, s4, 3
	s_add_i32 m0, s65, 0x18000
	v_lshl_add_u64 v[6:7], v[6:7], 0, s[26:27]
	s_lshl_b32 s9, s7, 13
	s_lshl_b32 s10, s1, 12
	s_waitcnt vmcnt(2) lgkmcnt(0)
	s_barrier
	global_load_lds_dwordx4 v[6:7], off
	v_lshl_add_u64 v[4:5], v[4:5], 0, s[26:27]
	s_add_i32 m0, s65, 0x1a000
	s_add_i32 s83, s65, 0x8000
	s_add_i32 s84, s65, 0xa000
	global_load_lds_dwordx4 v[4:5], off
	v_lshl_add_u64 v[0:1], v[0:1], 0, s[26:27]
	s_mov_b32 m0, s83
	s_add_u32 s4, s54, 0x40080
	global_load_lds_dwordx4 v[0:1], off
	v_lshl_add_u64 v[0:1], v[2:3], 0, s[26:27]
	s_mov_b32 m0, s84
	s_addc_u32 s5, s55, 0
	global_load_lds_dwordx4 v[0:1], off
	s_add_i32 m0, s65, 0x1c000
	v_lshl_add_u64 v[0:1], s[4:5], 0, v[134:135]
	global_load_lds_dwordx4 v[0:1], off
	v_lshl_add_u64 v[0:1], s[4:5], 0, v[138:139]
	s_add_i32 m0, s65, 0x1e000
	s_cmpk_lt_u32 s6, 0x100
	global_load_lds_dwordx4 v[0:1], off
	v_bfe_u32 v1, v128, 4, 2
	v_and_b32_e32 v0, 15, v128
	v_lshlrev_b32_e32 v3, 4, v1
	s_cselect_b64 s[28:29], -1, 0
	s_lshl_b32 s6, s7, 8
	v_lshl_or_b32 v131, s7, 6, v0
	v_lshl_or_b32 v4, v0, 6, v3
	v_lshlrev_b32_e32 v0, 2, v0
	s_add_i32 s6, s6, 0
	v_and_b32_e32 v5, 32, v0
	s_add_i32 s6, s6, 0x20000
	v_bitop3_b32 v4, v4, s9, v5 bitop3:0xde
	v_lshlrev_b32_e32 v5, 6, v128
	s_movk_i32 s4, 0x3c0
	v_add_u32_e32 v159, s6, v0
	v_lshlrev_b32_e32 v0, 8, v128
	v_lshlrev_b32_e32 v2, 3, v1
	v_and_or_b32 v3, v5, s4, v3
	v_cmp_eq_u32_e64 s[4:5], 0, v1
	v_and_b32_e32 v0, 0x38000, v0
	v_lshlrev_b32_e32 v1, 11, v11
	v_or3_b32 v0, v9, v0, v1
	v_add_u32_e32 v140, v0, v10
	v_lshlrev_b32_e32 v0, 4, v12
	v_and_b32_e32 v0, 0x78000, v0
	v_and_b32_e32 v5, 32, v8
	s_waitcnt vmcnt(6)
	v_or3_b32 v0, v9, v0, v1
	v_bitop3_b32 v157, s10, v3, v5 bitop3:0xf6
	v_lshl_or_b32 v158, s1, 5, v2
	s_lshl_b32 s1, s1, 15
	v_add_u32_e32 v142, v0, v10
	s_add_i32 s88, 0, 0x10000
	s_add_i32 s89, 0, 0x14000
	v_mbcnt_lo_u32_b32 v0, -1, 0
	s_or_b32 s85, s1, 0xfff00000
	s_or_b32 s86, s1, 0xfff20000
	v_mov_b32_e32 v141, v135
	v_mov_b32_e32 v143, v135
	v_mov_b64_e32 v[144:145], 0x600
	v_mov_b64_e32 v[146:147], 0x5ff
	s_movk_i32 s87, 0xc1
	v_add_u32_e32 v160, s88, v157
	v_add_u32_e32 v161, s89, v157
	v_add_u32_e32 v162, 0, v4
	s_movk_i32 s92, 0x1800
	v_mbcnt_hi_u32_b32 v163, -1, v0
	s_mov_b32 s1, 0
	s_mov_b32 s93, 0
	s_barrier
	s_branch .LBB0_652

.LBB0_1050:
	s_or_b64 exec, exec, s[0:1]
	s_cmpk_gt_i32 s2, 0xaff
	v_readfirstlane_b32 s5, v128
	s_cbranch_scc1 .LBB0_1066
	v_lshrrev_b32_e32 v0, 5, v128
	v_lshrrev_b32_e32 v2, 1, v128
	v_and_b32_e32 v0, 4, v0
	v_bfe_u32 v1, v128, 2, 2
	v_and_b32_e32 v12, 24, v2
	v_or3_b32 v0, v0, v1, v12
	v_lshlrev_b32_e32 v1, 4, v128
	v_add_u32_e32 v9, 0x2000, v1
	v_lshrrev_b32_e32 v2, 7, v9
	s_movk_i32 s0, 0xe0
	v_and_b32_e32 v4, 32, v128
	v_and_or_b32 v3, v2, s0, v0
	v_bitop3_b32 v10, v1, v4, 48 bitop3:0x6c
	v_and_b32_e32 v11, 64, v128
	v_bfe_u32 v13, v128, 2, 4
	s_movk_i32 s0, 0xf0
	s_lshr_b32 s6, s5, 6
	v_or_b32_e32 v1, v10, v11
	v_and_or_b32 v2, v2, s0, v13
	s_lshr_b32 s10, s5, 8
	s_lshl_b32 s48, s6, 10
	v_lshl_or_b32 v134, v2, 11, v1
	v_lshrrev_b32_e32 v2, 3, v128
	s_movk_i32 s0, 0x60
	s_add_u32 s49, s70, 0x2180000
	v_and_or_b32 v0, v2, s0, v0
	s_movk_i32 s0, 0x70
	s_addc_u32 s50, s71, 0
	v_lshl_or_b32 v136, v0, 11, v1
	v_and_or_b32 v0, v2, s0, v13
	s_lshr_b32 s0, s3, 29
	s_add_i32 s0, s2, s0
	s_ashr_i32 s1, s0, 3
	s_and_b32 s0, s0, -8
	s_sub_i32 s0, s2, s0
	s_cmp_lt_i32 s0, 0
	s_movk_i32 s51, 0x161
	s_cselect_b32 s4, s51, 0x160
	s_mul_i32 s0, s0, s4
	s_add_i32 s0, s0, s1
	s_mul_hi_i32 s1, s0, 0x2e8ba2e9
	s_lshr_b32 s4, s1, 31
	s_ashr_i32 s1, s1, 5
	s_add_i32 s1, s1, s4
	s_lshl_b32 s7, s1, 3
	s_mulk_i32 s1, 0xb0
	s_sub_i32 s0, s0, s1
	s_bfe_u32 s1, s0, 0x3001c
	s_add_i32 s1, s0, s1
	s_sext_i32_i16 s4, s1
	s_and_b32 s1, s1, 0xfff8
	s_sub_i32 s0, s0, s1
	s_sext_i32_i16 s0, s0
	s_lshr_b32 s4, s4, 3
	s_add_i32 s30, s7, s0
	s_ashr_i32 s31, s30, 31
	s_bfe_i64 s[8:9], s[4:5], 0x100000
	s_lshl_b64 s[0:1], s[30:31], 19
	s_lshl_b64 s[8:9], s[8:9], 19
	s_add_u32 s38, s49, s8
	s_addc_u32 s39, s50, s9
	s_add_i32 s31, s48, 0
	s_add_i32 m0, s31, 0x10000
	v_lshl_or_b32 v132, v3, 11, v1
	global_load_lds_dwordx4 v136, s[38:39]
	s_add_i32 m0, s31, 0x12000
	s_add_u32 s8, s38, 0x40000
	global_load_lds_dwordx4 v132, s[38:39]
	s_addc_u32 s9, s39, 0
	s_add_i32 m0, s31, 0x14000
	v_lshl_or_b32 v138, v0, 11, v1
	global_load_lds_dwordx4 v136, s[8:9]
	s_add_i32 m0, s31, 0x16000
	s_add_u32 s36, s14, s0
	s_addc_u32 s37, s15, s1
	s_add_i32 s52, s31, 0x2000
	global_load_lds_dwordx4 v132, s[8:9]
	s_mov_b32 m0, s31
	s_add_u32 s0, s36, 0x40000
	global_load_lds_dwordx4 v138, s[36:37]
	s_mov_b32 m0, s52
	s_addc_u32 s1, s37, 0
	s_add_i32 s53, s31, 0x4000
	global_load_lds_dwordx4 v134, s[36:37]
	s_mov_b32 m0, s53
	s_add_i32 s54, s31, 0x6000
	global_load_lds_dwordx4 v138, s[0:1]
	s_mov_b32 m0, s54
	v_mov_b32_e32 v137, 0
	global_load_lds_dwordx4 v134, s[0:1]
	v_and_b32_e32 v114, 0xff, v128
	s_lshr_b32 s98, s91, 2
	v_mov_b32_e32 v115, 0x358637bd
	s_mul_i32 s99, s98, s72
	s_add_i32 s99, s99, s2
	s_cmp_lt_u32 s99, 0xb00
	s_cselect_b32 s99, s99, s2
	s_and_b32 s100, s99, 7
	s_mul_i32 s100, s100, 0x160
	s_lshr_b32 s101, s99, 3
	s_add_i32 s100, s100, s101
	s_mul_hi_u32 s101, s100, 0x1745d18
	s_lshl_b32 s101, s101, 3
	s_and_b32 s100, s100, 7
	s_or_b32 s101, s101, s100
	s_lshl_b32 s101, s101, 8
	v_add_u32_e32 v112, s101, v114
	v_lshlrev_b32_e32 v112, 6, v112
	v_mov_b32_e32 v113, 0
	v_lshl_add_u64 v[112:113], s[18:19], 0, v[112:113]
	global_load_dwordx4 v[16:19], v[112:113], off
	global_load_dwordx4 v[20:23], v[112:113], off offset:16
	global_load_dwordx4 v[24:27], v[112:113], off offset:32
	global_load_dwordx4 v[28:31], v[112:113], off offset:48
	s_add_i32 s98, s98, 2
	s_mul_i32 s99, s98, s72
	s_add_i32 s99, s99, s2
	s_cmp_lt_u32 s99, 0xb00
	s_cselect_b32 s99, s99, s2
	s_and_b32 s100, s99, 7
	s_mul_i32 s100, s100, 0x160
	s_lshr_b32 s101, s99, 3
	s_add_i32 s100, s100, s101
	s_mul_hi_u32 s101, s100, 0x1745d18
	s_lshl_b32 s101, s101, 3
	s_and_b32 s100, s100, 7
	s_or_b32 s101, s101, s100
	s_lshl_b32 s101, s101, 8
	v_add_u32_e32 v112, s101, v114
	v_lshlrev_b32_e32 v112, 6, v112
	v_mov_b32_e32 v113, 0
	v_lshl_add_u64 v[112:113], s[18:19], 0, v[112:113]
	global_load_dwordx4 v[32:35], v[112:113], off
	global_load_dwordx4 v[36:39], v[112:113], off offset:16
	global_load_dwordx4 v[40:43], v[112:113], off offset:32
	global_load_dwordx4 v[44:47], v[112:113], off offset:48
	s_add_i32 s98, s98, 2
	s_mul_i32 s99, s98, s72
	s_add_i32 s99, s99, s2
	s_cmp_lt_u32 s99, 0xb00
	s_cselect_b32 s99, s99, s2
	s_and_b32 s100, s99, 7
	s_mul_i32 s100, s100, 0x160
	s_lshr_b32 s101, s99, 3
	s_add_i32 s100, s100, s101
	s_mul_hi_u32 s101, s100, 0x1745d18
	s_lshl_b32 s101, s101, 3
	s_and_b32 s100, s100, 7
	s_or_b32 s101, s101, s100
	s_lshl_b32 s101, s101, 8
	v_add_u32_e32 v112, s101, v114
	v_lshlrev_b32_e32 v112, 6, v112
	v_mov_b32_e32 v113, 0
	v_lshl_add_u64 v[112:113], s[18:19], 0, v[112:113]
	global_load_dwordx4 v[48:51], v[112:113], off
	global_load_dwordx4 v[52:55], v[112:113], off offset:16
	global_load_dwordx4 v[56:59], v[112:113], off offset:32
	global_load_dwordx4 v[60:63], v[112:113], off offset:48
	s_add_i32 s98, s98, 2
	s_mul_i32 s99, s98, s72
	s_add_i32 s99, s99, s2
	s_cmp_lt_u32 s99, 0xb00
	s_cselect_b32 s99, s99, s2
	s_and_b32 s100, s99, 7
	s_mul_i32 s100, s100, 0x160
	s_lshr_b32 s101, s99, 3
	s_add_i32 s100, s100, s101
	s_mul_hi_u32 s101, s100, 0x1745d18
	s_lshl_b32 s101, s101, 3
	s_and_b32 s100, s100, 7
	s_or_b32 s101, s101, s100
	s_lshl_b32 s101, s101, 8
	v_add_u32_e32 v112, s101, v114
	v_lshlrev_b32_e32 v112, 6, v112
	v_mov_b32_e32 v113, 0
	v_lshl_add_u64 v[112:113], s[18:19], 0, v[112:113]
	global_load_dwordx4 v[64:67], v[112:113], off
	global_load_dwordx4 v[68:71], v[112:113], off offset:16
	global_load_dwordx4 v[72:75], v[112:113], off offset:32
	global_load_dwordx4 v[76:79], v[112:113], off offset:48
	s_add_i32 s98, s98, 2
	s_mul_i32 s99, s98, s72
	s_add_i32 s99, s99, s2
	s_cmp_lt_u32 s99, 0xb00
	s_cselect_b32 s99, s99, s2
	s_and_b32 s100, s99, 7
	s_mul_i32 s100, s100, 0x160
	s_lshr_b32 s101, s99, 3
	s_add_i32 s100, s100, s101
	s_mul_hi_u32 s101, s100, 0x1745d18
	s_lshl_b32 s101, s101, 3
	s_and_b32 s100, s100, 7
	s_or_b32 s101, s101, s100
	s_lshl_b32 s101, s101, 8
	v_add_u32_e32 v112, s101, v114
	v_lshlrev_b32_e32 v112, 6, v112
	v_mov_b32_e32 v113, 0
	v_lshl_add_u64 v[112:113], s[18:19], 0, v[112:113]
	global_load_dwordx4 v[80:83], v[112:113], off
	global_load_dwordx4 v[84:87], v[112:113], off offset:16
	global_load_dwordx4 v[88:91], v[112:113], off offset:32
	global_load_dwordx4 v[92:95], v[112:113], off offset:48
	s_add_i32 s98, s98, 2
	s_mul_i32 s99, s98, s72
	s_add_i32 s99, s99, s2
	s_cmp_lt_u32 s99, 0xb00
	s_cselect_b32 s99, s99, s2
	s_and_b32 s100, s99, 7
	s_mul_i32 s100, s100, 0x160
	s_lshr_b32 s101, s99, 3
	s_add_i32 s100, s100, s101
	s_mul_hi_u32 s101, s100, 0x1745d18
	s_lshl_b32 s101, s101, 3
	s_and_b32 s100, s100, 7
	s_or_b32 s101, s101, s100
	s_lshl_b32 s101, s101, 8
	v_add_u32_e32 v112, s101, v114
	v_lshlrev_b32_e32 v112, 6, v112
	v_mov_b32_e32 v113, 0
	v_lshl_add_u64 v[112:113], s[18:19], 0, v[112:113]
	global_load_dwordx4 v[96:99], v[112:113], off
	global_load_dwordx4 v[100:103], v[112:113], off offset:16
	global_load_dwordx4 v[104:107], v[112:113], off offset:32
	global_load_dwordx4 v[108:111], v[112:113], off offset:48
	s_add_i32 s98, s98, 2
	v_lshlrev_b32_e32 v116, 2, v128
	v_add_u32_e32 v116, 0x20000, v116
	s_waitcnt vmcnt(20)
	v_pk_add_f32 v[118:119], v[18:19], v[22:23]
	v_pk_add_f32 v[120:121], v[16:17], v[20:21]
	v_pk_add_f32 v[122:123], v[26:27], v[30:31]
	v_pk_add_f32 v[124:125], v[24:25], v[28:29]
	v_pk_add_f32 v[118:119], v[118:119], v[122:123]
	v_pk_add_f32 v[120:121], v[120:121], v[124:125]
	v_add_f32_e32 v120, v121, v120
	v_add_f32_e32 v118, v118, v119
	v_add_f32_e32 v118, v120, v118
	v_fmamk_f32 v118, v118, 0x3a800000, v115
	v_rsq_f32_e32 v118, v118
	ds_write_b32 v116, v118
	s_waitcnt vmcnt(16)
	v_pk_add_f32 v[118:119], v[34:35], v[38:39]
	v_pk_add_f32 v[120:121], v[32:33], v[36:37]
	v_pk_add_f32 v[122:123], v[42:43], v[46:47]
	v_pk_add_f32 v[124:125], v[40:41], v[44:45]
	v_pk_add_f32 v[118:119], v[118:119], v[122:123]
	v_pk_add_f32 v[120:121], v[120:121], v[124:125]
	v_add_f32_e32 v120, v121, v120
	v_add_f32_e32 v118, v118, v119
	v_add_f32_e32 v118, v120, v118
	v_fmamk_f32 v118, v118, 0x3a800000, v115
	v_rsq_f32_e32 v118, v118
	ds_write_b32 v116, v118 offset:2048
	s_waitcnt vmcnt(12)
	v_pk_add_f32 v[118:119], v[50:51], v[54:55]
	v_pk_add_f32 v[120:121], v[48:49], v[52:53]
	v_pk_add_f32 v[122:123], v[58:59], v[62:63]
	v_pk_add_f32 v[124:125], v[56:57], v[60:61]
	v_pk_add_f32 v[118:119], v[118:119], v[122:123]
	v_pk_add_f32 v[120:121], v[120:121], v[124:125]
	v_add_f32_e32 v120, v121, v120
	v_add_f32_e32 v118, v118, v119
	v_add_f32_e32 v118, v120, v118
	v_fmamk_f32 v118, v118, 0x3a800000, v115
	v_rsq_f32_e32 v118, v118
	ds_write_b32 v116, v118 offset:4096
	s_waitcnt vmcnt(8)
	v_pk_add_f32 v[118:119], v[66:67], v[70:71]
	v_pk_add_f32 v[120:121], v[64:65], v[68:69]
	v_pk_add_f32 v[122:123], v[74:75], v[78:79]
	v_pk_add_f32 v[124:125], v[72:73], v[76:77]
	v_pk_add_f32 v[118:119], v[118:119], v[122:123]
	v_pk_add_f32 v[120:121], v[120:121], v[124:125]
	v_add_f32_e32 v120, v121, v120
	v_add_f32_e32 v118, v118, v119
	v_add_f32_e32 v118, v120, v118
	v_fmamk_f32 v118, v118, 0x3a800000, v115
	v_rsq_f32_e32 v118, v118
	ds_write_b32 v116, v118 offset:6144
	s_waitcnt vmcnt(4)
	v_pk_add_f32 v[118:119], v[82:83], v[86:87]
	v_pk_add_f32 v[120:121], v[80:81], v[84:85]
	v_pk_add_f32 v[122:123], v[90:91], v[94:95]
	v_pk_add_f32 v[124:125], v[88:89], v[92:93]
	v_pk_add_f32 v[118:119], v[118:119], v[122:123]
	v_pk_add_f32 v[120:121], v[120:121], v[124:125]
	v_add_f32_e32 v120, v121, v120
	v_add_f32_e32 v118, v118, v119
	v_add_f32_e32 v118, v120, v118
	v_fmamk_f32 v118, v118, 0x3a800000, v115
	v_rsq_f32_e32 v118, v118
	ds_write_b32 v116, v118 offset:8192
	s_waitcnt vmcnt(0)
	v_pk_add_f32 v[118:119], v[98:99], v[102:103]
	v_pk_add_f32 v[120:121], v[96:97], v[100:101]
	v_pk_add_f32 v[122:123], v[106:107], v[110:111]
	v_pk_add_f32 v[124:125], v[104:105], v[108:109]
	v_pk_add_f32 v[118:119], v[118:119], v[122:123]
	v_pk_add_f32 v[120:121], v[120:121], v[124:125]
	v_add_f32_e32 v120, v121, v120
	v_add_f32_e32 v118, v118, v119
	v_add_f32_e32 v118, v120, v118
	v_fmamk_f32 v118, v118, 0x3a800000, v115
	v_rsq_f32_e32 v118, v118
	ds_write_b32 v116, v118 offset:10240
	v_mov_b32_e32 v133, v137
	v_mov_b32_e32 v139, v137
	v_mov_b32_e32 v135, v137
	s_cmp_eq_u32 s10, 1
	s_mov_b32 s12, 0
	v_lshl_add_u64 v[6:7], s[38:39], 0, v[136:137]
	v_lshl_add_u64 v[4:5], s[38:39], 0, v[132:133]
	v_lshl_add_u64 v[0:1], s[36:37], 0, v[138:139]
	s_cselect_b64 s[0:1], -1, 0
	s_cmp_lg_u32 s10, 1
	v_lshl_add_u64 v[2:3], s[36:37], 0, v[134:135]
	s_cbranch_scc1 .LBB0_1053
	s_barrier
.LBB0_1053:
	s_lshl_b32 s6, s6, 5
	s_and_b32 s22, s6, 0x60
	s_mov_b64 s[6:7], 0x80
	s_add_i32 m0, s31, 0x18000
	v_lshl_add_u64 v[6:7], v[6:7], 0, s[6:7]
	s_lshl_b32 s11, s10, 13
	s_lshl_b32 s23, s22, 7
	s_waitcnt vmcnt(2) lgkmcnt(0)
	s_barrier
	global_load_lds_dwordx4 v[6:7], off
	v_lshl_add_u64 v[4:5], v[4:5], 0, s[6:7]
	s_add_i32 m0, s31, 0x1a000
	s_add_i32 s55, s31, 0x8000
	s_add_i32 s56, s31, 0xa000
	global_load_lds_dwordx4 v[4:5], off
	v_lshl_add_u64 v[0:1], v[0:1], 0, s[6:7]
	s_mov_b32 m0, s55
	s_add_u32 s8, s38, 0x40080
	global_load_lds_dwordx4 v[0:1], off
	v_lshl_add_u64 v[0:1], v[2:3], 0, s[6:7]
	s_mov_b32 m0, s56
	s_addc_u32 s9, s39, 0
	global_load_lds_dwordx4 v[0:1], off
	s_add_i32 m0, s31, 0x1c000
	v_lshl_add_u64 v[0:1], s[8:9], 0, v[136:137]
	global_load_lds_dwordx4 v[0:1], off
	v_lshl_add_u64 v[0:1], s[8:9], 0, v[132:133]
	s_add_i32 m0, s31, 0x1e000
	s_sext_i32_i16 s13, s4
	global_load_lds_dwordx4 v[0:1], off
	v_and_b32_e32 v0, 15, v128
	v_lshlrev_b32_e32 v1, 1, v12
	v_lshl_or_b32 v131, s10, 6, v0
	v_lshl_or_b32 v2, v0, 6, v1
	v_lshlrev_b32_e32 v0, 2, v0
	v_and_b32_e32 v3, 32, v0
	v_bitop3_b32 v2, v2, s11, v3 bitop3:0xde
	v_lshlrev_b32_e32 v3, 6, v128
	s_movk_i32 s4, 0x3c0
	s_cmpk_lt_u32 s5, 0x100
	v_and_or_b32 v1, v3, s4, v1
	s_cselect_b64 s[8:9], -1, 0
	s_lshl_b32 s4, s10, 8
	s_add_i32 s4, s4, 0
	s_add_i32 s4, s4, 0x20000
	v_and_b32_e32 v3, 32, v8
	v_add_u32_e32 v153, s4, v0
	v_lshlrev_b32_e32 v0, 8, v128
	v_bitop3_b32 v152, s23, v1, v3 bitop3:0xf6
	v_and_b32_e32 v0, 0x38000, v0
	v_lshlrev_b32_e32 v1, 11, v13
	v_or3_b32 v0, v10, v0, v1
	v_add_u32_e32 v140, v0, v11
	v_lshlrev_b32_e32 v0, 4, v9
	s_waitcnt vmcnt(6)
	v_and_b32_e32 v0, 0x78000, v0
	v_or3_b32 v0, v10, v0, v1
	s_add_i32 s57, 0, 0x10000
	s_add_i32 s58, 0, 0x14000
	v_or_b32_e32 v154, s22, v12
	v_mov_b32_e32 v141, v137
	v_add_u32_e32 v142, v0, v11
	v_mov_b32_e32 v143, v137
	v_mov_b64_e32 v[144:145], 0xb00
	v_mov_b64_e32 v[146:147], 0xaff
	v_add_u32_e32 v155, s57, v152
	v_add_u32_e32 v157, s58, v152
	v_add_u32_e32 v158, 0, v2
	s_movk_i32 s59, 0x1600
	s_mov_b32 s62, 0
	s_barrier
	s_branch .LBB0_1056

.LBB0_1226:
	s_or_b64 exec, exec, s[0:1]
	s_cmpk_gt_i32 s2, 0x5ff
	v_readfirstlane_b32 s5, v128
	s_cbranch_scc1 .LBB0_1242
	v_lshrrev_b32_e32 v0, 5, v128
	v_lshrrev_b32_e32 v2, 1, v128
	v_and_b32_e32 v0, 4, v0
	v_bfe_u32 v1, v128, 2, 2
	v_and_b32_e32 v12, 24, v2
	v_or3_b32 v0, v0, v1, v12
	v_lshlrev_b32_e32 v1, 4, v128
	v_add_u32_e32 v9, 0x2000, v1
	v_lshrrev_b32_e32 v2, 7, v9
	s_movk_i32 s0, 0xe0
	v_and_b32_e32 v4, 32, v128
	v_and_or_b32 v3, v2, s0, v0
	v_bitop3_b32 v10, v1, v4, 48 bitop3:0x6c
	v_and_b32_e32 v11, 64, v128
	v_bfe_u32 v13, v128, 2, 4
	s_movk_i32 s0, 0xf0
	s_lshr_b32 s6, s5, 6
	v_or_b32_e32 v1, v10, v11
	v_and_or_b32 v2, v2, s0, v13
	s_lshr_b32 s10, s5, 8
	s_lshl_b32 s48, s6, 10
	v_lshl_or_b32 v134, v2, 11, v1
	v_lshrrev_b32_e32 v2, 3, v128
	s_movk_i32 s0, 0x60
	s_add_u32 s49, s70, 0x3200000
	v_and_or_b32 v0, v2, s0, v0
	s_movk_i32 s0, 0x70
	s_addc_u32 s50, s71, 0
	v_lshl_or_b32 v136, v0, 11, v1
	v_and_or_b32 v0, v2, s0, v13
	s_lshr_b32 s0, s3, 29
	s_add_i32 s0, s2, s0
	s_ashr_i32 s1, s0, 3
	s_and_b32 s0, s0, -8
	s_sub_i32 s0, s2, s0
	s_cmp_lt_i32 s0, 0
	s_movk_i32 s51, 0xc1
	s_cselect_b32 s4, s51, 0xc0
	s_mul_i32 s0, s0, s4
	s_add_i32 s0, s0, s1
	s_mul_hi_i32 s1, s0, 0x2aaaaaab
	s_lshr_b32 s4, s1, 31
	s_ashr_i32 s1, s1, 4
	s_add_i32 s1, s1, s4
	s_lshl_b32 s7, s1, 3
	s_mulk_i32 s1, 0x60
	s_sub_i32 s0, s0, s1
	s_bfe_i32 s1, s0, 0x80000
	s_bfe_u32 s1, s1, 0x3000c
	s_add_i32 s1, s0, s1
	s_bfe_i32 s4, s1, 0x80000
	s_and_b32 s1, s1, 0xf8
	s_sub_i32 s0, s0, s1
	s_sext_i32_i16 s4, s4
	s_sext_i32_i8 s0, s0
	s_lshr_b32 s4, s4, 3
	s_add_i32 s30, s7, s0
	s_ashr_i32 s31, s30, 31
	s_bfe_i64 s[8:9], s[4:5], 0x100000
	s_lshl_b64 s[0:1], s[30:31], 19
	s_lshl_b64 s[8:9], s[8:9], 19
	s_add_u32 s38, s49, s8
	s_addc_u32 s39, s50, s9
	s_add_i32 s31, s48, 0
	s_add_i32 m0, s31, 0x10000
	v_lshl_or_b32 v132, v3, 11, v1
	global_load_lds_dwordx4 v136, s[38:39]
	s_add_i32 m0, s31, 0x12000
	s_add_u32 s8, s38, 0x40000
	global_load_lds_dwordx4 v132, s[38:39]
	s_addc_u32 s9, s39, 0
	s_add_i32 m0, s31, 0x14000
	v_lshl_or_b32 v138, v0, 11, v1
	global_load_lds_dwordx4 v136, s[8:9]
	s_add_i32 m0, s31, 0x16000
	s_add_u32 s36, s14, s0
	s_addc_u32 s37, s15, s1
	s_add_i32 s52, s31, 0x2000
	global_load_lds_dwordx4 v132, s[8:9]
	s_mov_b32 m0, s31
	s_add_u32 s0, s36, 0x40000
	global_load_lds_dwordx4 v138, s[36:37]
	s_mov_b32 m0, s52
	s_addc_u32 s1, s37, 0
	s_add_i32 s53, s31, 0x4000
	global_load_lds_dwordx4 v134, s[36:37]
	s_mov_b32 m0, s53
	s_add_i32 s54, s31, 0x6000
	global_load_lds_dwordx4 v138, s[0:1]
	s_mov_b32 m0, s54
	v_mov_b32_e32 v137, 0
	global_load_lds_dwordx4 v134, s[0:1]
	v_and_b32_e32 v114, 0xff, v128
	s_lshr_b32 s98, s91, 2
	v_mov_b32_e32 v115, 0x358637bd
	s_mul_i32 s99, s98, s72
	s_add_i32 s99, s99, s2
	s_cmp_lt_u32 s99, 0x600
	s_cselect_b32 s99, s99, s2
	s_and_b32 s100, s99, 7
	s_mul_i32 s100, s100, 0xc0
	s_lshr_b32 s101, s99, 3
	s_add_i32 s100, s100, s101
	s_mul_hi_u32 s101, s100, 0x2aaaaab
	s_lshl_b32 s101, s101, 3
	s_and_b32 s100, s100, 7
	s_or_b32 s101, s101, s100
	s_lshl_b32 s101, s101, 8
	v_add_u32_e32 v112, s101, v114
	v_lshlrev_b32_e32 v112, 6, v112
	v_mov_b32_e32 v113, 0
	v_lshl_add_u64 v[112:113], s[18:19], 0, v[112:113]
	global_load_dwordx4 v[16:19], v[112:113], off
	global_load_dwordx4 v[20:23], v[112:113], off offset:16
	global_load_dwordx4 v[24:27], v[112:113], off offset:32
	global_load_dwordx4 v[28:31], v[112:113], off offset:48
	s_add_i32 s98, s98, 2
	s_mul_i32 s99, s98, s72
	s_add_i32 s99, s99, s2
	s_cmp_lt_u32 s99, 0x600
	s_cselect_b32 s99, s99, s2
	s_and_b32 s100, s99, 7
	s_mul_i32 s100, s100, 0xc0
	s_lshr_b32 s101, s99, 3
	s_add_i32 s100, s100, s101
	s_mul_hi_u32 s101, s100, 0x2aaaaab
	s_lshl_b32 s101, s101, 3
	s_and_b32 s100, s100, 7
	s_or_b32 s101, s101, s100
	s_lshl_b32 s101, s101, 8
	v_add_u32_e32 v112, s101, v114
	v_lshlrev_b32_e32 v112, 6, v112
	v_mov_b32_e32 v113, 0
	v_lshl_add_u64 v[112:113], s[18:19], 0, v[112:113]
	global_load_dwordx4 v[32:35], v[112:113], off
	global_load_dwordx4 v[36:39], v[112:113], off offset:16
	global_load_dwordx4 v[40:43], v[112:113], off offset:32
	global_load_dwordx4 v[44:47], v[112:113], off offset:48
	s_add_i32 s98, s98, 2
	s_mul_i32 s99, s98, s72
	s_add_i32 s99, s99, s2
	s_cmp_lt_u32 s99, 0x600
	s_cselect_b32 s99, s99, s2
	s_and_b32 s100, s99, 7
	s_mul_i32 s100, s100, 0xc0
	s_lshr_b32 s101, s99, 3
	s_add_i32 s100, s100, s101
	s_mul_hi_u32 s101, s100, 0x2aaaaab
	s_lshl_b32 s101, s101, 3
	s_and_b32 s100, s100, 7
	s_or_b32 s101, s101, s100
	s_lshl_b32 s101, s101, 8
	v_add_u32_e32 v112, s101, v114
	v_lshlrev_b32_e32 v112, 6, v112
	v_mov_b32_e32 v113, 0
	v_lshl_add_u64 v[112:113], s[18:19], 0, v[112:113]
	global_load_dwordx4 v[48:51], v[112:113], off
	global_load_dwordx4 v[52:55], v[112:113], off offset:16
	global_load_dwordx4 v[56:59], v[112:113], off offset:32
	global_load_dwordx4 v[60:63], v[112:113], off offset:48
	s_add_i32 s98, s98, 2
	v_lshlrev_b32_e32 v116, 2, v128
	v_add_u32_e32 v116, 0x20000, v116
	s_waitcnt vmcnt(8)
	v_pk_add_f32 v[118:119], v[18:19], v[22:23]
	v_pk_add_f32 v[120:121], v[16:17], v[20:21]
	v_pk_add_f32 v[122:123], v[26:27], v[30:31]
	v_pk_add_f32 v[124:125], v[24:25], v[28:29]
	v_pk_add_f32 v[118:119], v[118:119], v[122:123]
	v_pk_add_f32 v[120:121], v[120:121], v[124:125]
	v_add_f32_e32 v120, v121, v120
	v_add_f32_e32 v118, v118, v119
	v_add_f32_e32 v118, v120, v118
	v_fmamk_f32 v118, v118, 0x3a800000, v115
	v_rsq_f32_e32 v118, v118
	ds_write_b32 v116, v118
	s_waitcnt vmcnt(4)
	v_pk_add_f32 v[118:119], v[34:35], v[38:39]
	v_pk_add_f32 v[120:121], v[32:33], v[36:37]
	v_pk_add_f32 v[122:123], v[42:43], v[46:47]
	v_pk_add_f32 v[124:125], v[40:41], v[44:45]
	v_pk_add_f32 v[118:119], v[118:119], v[122:123]
	v_pk_add_f32 v[120:121], v[120:121], v[124:125]
	v_add_f32_e32 v120, v121, v120
	v_add_f32_e32 v118, v118, v119
	v_add_f32_e32 v118, v120, v118
	v_fmamk_f32 v118, v118, 0x3a800000, v115
	v_rsq_f32_e32 v118, v118
	ds_write_b32 v116, v118 offset:2048
	s_waitcnt vmcnt(0)
	v_pk_add_f32 v[118:119], v[50:51], v[54:55]
	v_pk_add_f32 v[120:121], v[48:49], v[52:53]
	v_pk_add_f32 v[122:123], v[58:59], v[62:63]
	v_pk_add_f32 v[124:125], v[56:57], v[60:61]
	v_pk_add_f32 v[118:119], v[118:119], v[122:123]
	v_pk_add_f32 v[120:121], v[120:121], v[124:125]
	v_add_f32_e32 v120, v121, v120
	v_add_f32_e32 v118, v118, v119
	v_add_f32_e32 v118, v120, v118
	v_fmamk_f32 v118, v118, 0x3a800000, v115
	v_rsq_f32_e32 v118, v118
	ds_write_b32 v116, v118 offset:4096
	v_mov_b32_e32 v133, v137
	v_mov_b32_e32 v139, v137
	v_mov_b32_e32 v135, v137
	s_cmp_eq_u32 s10, 1
	s_mov_b32 s62, 0
	v_lshl_add_u64 v[6:7], s[38:39], 0, v[136:137]
	v_lshl_add_u64 v[4:5], s[38:39], 0, v[132:133]
	v_lshl_add_u64 v[0:1], s[36:37], 0, v[138:139]
	s_cselect_b64 s[0:1], -1, 0
	s_cmp_lg_u32 s10, 1
	v_lshl_add_u64 v[2:3], s[36:37], 0, v[134:135]
	s_cbranch_scc1 .LBB0_1229
	s_barrier
.LBB0_1229:
	s_lshl_b32 s6, s6, 5
	s_and_b32 s22, s6, 0x60
	s_mov_b64 s[6:7], 0x80
	s_add_i32 m0, s31, 0x18000
	v_lshl_add_u64 v[6:7], v[6:7], 0, s[6:7]
	s_lshl_b32 s11, s10, 13
	s_lshl_b32 s23, s22, 7
	s_waitcnt vmcnt(2) lgkmcnt(0)
	s_barrier
	global_load_lds_dwordx4 v[6:7], off
	v_lshl_add_u64 v[4:5], v[4:5], 0, s[6:7]
	s_add_i32 m0, s31, 0x1a000
	s_add_i32 s12, s31, 0x8000
	s_add_i32 s13, s31, 0xa000
	global_load_lds_dwordx4 v[4:5], off
	v_lshl_add_u64 v[0:1], v[0:1], 0, s[6:7]
	s_mov_b32 m0, s12
	s_add_u32 s8, s38, 0x40080
	global_load_lds_dwordx4 v[0:1], off
	v_lshl_add_u64 v[0:1], v[2:3], 0, s[6:7]
	s_mov_b32 m0, s13
	s_addc_u32 s9, s39, 0
	global_load_lds_dwordx4 v[0:1], off
	s_add_i32 m0, s31, 0x1c000
	v_lshl_add_u64 v[0:1], s[8:9], 0, v[136:137]
	global_load_lds_dwordx4 v[0:1], off
	v_lshl_add_u64 v[0:1], s[8:9], 0, v[132:133]
	s_add_i32 m0, s31, 0x1e000
	s_sext_i32_i8 s63, s4
	global_load_lds_dwordx4 v[0:1], off
	v_and_b32_e32 v0, 15, v128
	v_lshlrev_b32_e32 v1, 1, v12
	v_lshl_or_b32 v131, s10, 6, v0
	v_lshl_or_b32 v2, v0, 6, v1
	v_lshlrev_b32_e32 v0, 2, v0
	v_and_b32_e32 v3, 32, v0
	v_bitop3_b32 v2, v2, s11, v3 bitop3:0xde
	v_lshlrev_b32_e32 v3, 6, v128
	s_movk_i32 s4, 0x3c0
	s_cmpk_lt_u32 s5, 0x100
	v_and_or_b32 v1, v3, s4, v1
	s_cselect_b64 s[8:9], -1, 0
	s_lshl_b32 s4, s10, 8
	s_add_i32 s4, s4, 0
	s_add_i32 s4, s4, 0x20000
	v_and_b32_e32 v3, 32, v8
	v_add_u32_e32 v153, s4, v0
	v_lshlrev_b32_e32 v0, 8, v128
	v_bitop3_b32 v152, s23, v1, v3 bitop3:0xf6
	v_and_b32_e32 v0, 0x38000, v0
	v_lshlrev_b32_e32 v1, 11, v13
	v_or3_b32 v0, v10, v0, v1
	v_add_u32_e32 v140, v0, v11
	v_lshlrev_b32_e32 v0, 4, v9
	s_waitcnt vmcnt(6)
	v_and_b32_e32 v0, 0x78000, v0
	v_or3_b32 v0, v10, v0, v1
	s_add_i32 s55, 0, 0x10000
	s_add_i32 s56, 0, 0x14000
	v_or_b32_e32 v154, s22, v12
	v_mov_b32_e32 v141, v137
	v_add_u32_e32 v142, v0, v11
	v_mov_b32_e32 v143, v137
	v_mov_b64_e32 v[144:145], 0x600
	v_mov_b64_e32 v[146:147], 0x5ff
	v_add_u32_e32 v155, s55, v152
	v_add_u32_e32 v157, s56, v152
	v_add_u32_e32 v158, 0, v2
	s_movk_i32 s57, 0x1800
	s_mov_b32 s58, 0
	s_barrier
	s_branch .LBB0_1232

.LBB0_1638:
	s_or_b64 exec, exec, s[0:1]
	s_cmpk_gt_i32 s2, 0xaff
	v_readfirstlane_b32 s5, v128
	s_cbranch_scc1 .LBB0_1654
	v_lshrrev_b32_e32 v0, 5, v128
	v_lshrrev_b32_e32 v2, 1, v128
	v_and_b32_e32 v0, 4, v0
	v_bfe_u32 v1, v128, 2, 2
	v_and_b32_e32 v12, 24, v2
	v_or3_b32 v0, v0, v1, v12
	v_lshlrev_b32_e32 v1, 4, v128
	v_add_u32_e32 v9, 0x2000, v1
	v_lshrrev_b32_e32 v2, 7, v9
	s_movk_i32 s0, 0xe0
	v_and_b32_e32 v4, 32, v128
	v_and_or_b32 v3, v2, s0, v0
	v_bitop3_b32 v10, v1, v4, 48 bitop3:0x6c
	v_and_b32_e32 v11, 64, v128
	v_bfe_u32 v13, v128, 2, 4
	s_movk_i32 s0, 0xf0
	s_lshr_b32 s6, s5, 6
	v_or_b32_e32 v1, v10, v11
	v_and_or_b32 v2, v2, s0, v13
	s_lshr_b32 s10, s5, 8
	s_lshl_b32 s44, s6, 10
	v_lshl_or_b32 v132, v2, 11, v1
	v_lshrrev_b32_e32 v2, 3, v128
	s_movk_i32 s0, 0x60
	s_add_u32 s45, s70, 0x3a00000
	v_and_or_b32 v0, v2, s0, v0
	s_movk_i32 s0, 0x70
	s_addc_u32 s46, s71, 0
	v_lshl_or_b32 v134, v0, 11, v1
	v_and_or_b32 v0, v2, s0, v13
	s_lshr_b32 s0, s3, 29
	s_add_i32 s0, s2, s0
	s_ashr_i32 s1, s0, 3
	s_and_b32 s0, s0, -8
	s_sub_i32 s0, s2, s0
	s_cmp_lt_i32 s0, 0
	s_movk_i32 s47, 0x161
	s_cselect_b32 s4, s47, 0x160
	s_mul_i32 s0, s0, s4
	s_add_i32 s0, s0, s1
	s_mul_hi_i32 s1, s0, 0x2e8ba2e9
	s_lshr_b32 s4, s1, 31
	s_ashr_i32 s1, s1, 5
	s_add_i32 s1, s1, s4
	s_lshl_b32 s7, s1, 3
	s_mulk_i32 s1, 0xb0
	s_sub_i32 s0, s0, s1
	s_bfe_u32 s1, s0, 0x3001c
	s_add_i32 s1, s0, s1
	s_sext_i32_i16 s4, s1
	s_and_b32 s1, s1, 0xfff8
	s_sub_i32 s0, s0, s1
	s_sext_i32_i16 s0, s0
	s_lshr_b32 s4, s4, 3
	s_add_i32 s30, s7, s0
	s_ashr_i32 s31, s30, 31
	s_bfe_i64 s[8:9], s[4:5], 0x100000
	s_lshl_b64 s[0:1], s[30:31], 19
	s_lshl_b64 s[8:9], s[8:9], 19
	s_add_u32 s38, s45, s8
	s_addc_u32 s39, s46, s9
	s_add_i32 s31, s44, 0
	s_add_i32 m0, s31, 0x10000
	v_lshl_or_b32 v130, v3, 11, v1
	global_load_lds_dwordx4 v134, s[38:39]
	s_add_i32 m0, s31, 0x12000
	s_add_u32 s8, s38, 0x40000
	global_load_lds_dwordx4 v130, s[38:39]
	s_addc_u32 s9, s39, 0
	s_add_i32 m0, s31, 0x14000
	v_lshl_or_b32 v136, v0, 11, v1
	global_load_lds_dwordx4 v134, s[8:9]
	s_add_i32 m0, s31, 0x16000
	s_add_u32 s36, s14, s0
	s_addc_u32 s37, s15, s1
	s_add_i32 s48, s31, 0x2000
	global_load_lds_dwordx4 v130, s[8:9]
	s_mov_b32 m0, s31
	s_add_u32 s0, s36, 0x40000
	global_load_lds_dwordx4 v136, s[36:37]
	s_mov_b32 m0, s48
	s_addc_u32 s1, s37, 0
	s_add_i32 s49, s31, 0x4000
	global_load_lds_dwordx4 v132, s[36:37]
	s_mov_b32 m0, s49
	s_add_i32 s50, s31, 0x6000
	global_load_lds_dwordx4 v136, s[0:1]
	s_mov_b32 m0, s50
	v_mov_b32_e32 v135, 0
	global_load_lds_dwordx4 v132, s[0:1]
	v_and_b32_e32 v114, 0xff, v128
	s_lshr_b32 s98, s91, 2
	v_mov_b32_e32 v115, 0x358637bd
	s_mul_i32 s99, s98, s72
	s_add_i32 s99, s99, s2
	s_cmp_lt_u32 s99, 0xb00
	s_cselect_b32 s99, s99, s2
	s_and_b32 s100, s99, 7
	s_mul_i32 s100, s100, 0x160
	s_lshr_b32 s101, s99, 3
	s_add_i32 s100, s100, s101
	s_mul_hi_u32 s101, s100, 0x1745d18
	s_lshl_b32 s101, s101, 3
	s_and_b32 s100, s100, 7
	s_or_b32 s101, s101, s100
	s_lshl_b32 s101, s101, 8
	v_add_u32_e32 v112, s101, v114
	v_lshlrev_b32_e32 v112, 6, v112
	v_mov_b32_e32 v113, 0
	v_lshl_add_u64 v[112:113], s[18:19], 0, v[112:113]
	global_load_dwordx4 v[16:19], v[112:113], off
	global_load_dwordx4 v[20:23], v[112:113], off offset:16
	global_load_dwordx4 v[24:27], v[112:113], off offset:32
	global_load_dwordx4 v[28:31], v[112:113], off offset:48
	s_add_i32 s98, s98, 2
	s_mul_i32 s99, s98, s72
	s_add_i32 s99, s99, s2
	s_cmp_lt_u32 s99, 0xb00
	s_cselect_b32 s99, s99, s2
	s_and_b32 s100, s99, 7
	s_mul_i32 s100, s100, 0x160
	s_lshr_b32 s101, s99, 3
	s_add_i32 s100, s100, s101
	s_mul_hi_u32 s101, s100, 0x1745d18
	s_lshl_b32 s101, s101, 3
	s_and_b32 s100, s100, 7
	s_or_b32 s101, s101, s100
	s_lshl_b32 s101, s101, 8
	v_add_u32_e32 v112, s101, v114
	v_lshlrev_b32_e32 v112, 6, v112
	v_mov_b32_e32 v113, 0
	v_lshl_add_u64 v[112:113], s[18:19], 0, v[112:113]
	global_load_dwordx4 v[32:35], v[112:113], off
	global_load_dwordx4 v[36:39], v[112:113], off offset:16
	global_load_dwordx4 v[40:43], v[112:113], off offset:32
	global_load_dwordx4 v[44:47], v[112:113], off offset:48
	s_add_i32 s98, s98, 2
	s_mul_i32 s99, s98, s72
	s_add_i32 s99, s99, s2
	s_cmp_lt_u32 s99, 0xb00
	s_cselect_b32 s99, s99, s2
	s_and_b32 s100, s99, 7
	s_mul_i32 s100, s100, 0x160
	s_lshr_b32 s101, s99, 3
	s_add_i32 s100, s100, s101
	s_mul_hi_u32 s101, s100, 0x1745d18
	s_lshl_b32 s101, s101, 3
	s_and_b32 s100, s100, 7
	s_or_b32 s101, s101, s100
	s_lshl_b32 s101, s101, 8
	v_add_u32_e32 v112, s101, v114
	v_lshlrev_b32_e32 v112, 6, v112
	v_mov_b32_e32 v113, 0
	v_lshl_add_u64 v[112:113], s[18:19], 0, v[112:113]
	global_load_dwordx4 v[48:51], v[112:113], off
	global_load_dwordx4 v[52:55], v[112:113], off offset:16
	global_load_dwordx4 v[56:59], v[112:113], off offset:32
	global_load_dwordx4 v[60:63], v[112:113], off offset:48
	s_add_i32 s98, s98, 2
	s_mul_i32 s99, s98, s72
	s_add_i32 s99, s99, s2
	s_cmp_lt_u32 s99, 0xb00
	s_cselect_b32 s99, s99, s2
	s_and_b32 s100, s99, 7
	s_mul_i32 s100, s100, 0x160
	s_lshr_b32 s101, s99, 3
	s_add_i32 s100, s100, s101
	s_mul_hi_u32 s101, s100, 0x1745d18
	s_lshl_b32 s101, s101, 3
	s_and_b32 s100, s100, 7
	s_or_b32 s101, s101, s100
	s_lshl_b32 s101, s101, 8
	v_add_u32_e32 v112, s101, v114
	v_lshlrev_b32_e32 v112, 6, v112
	v_mov_b32_e32 v113, 0
	v_lshl_add_u64 v[112:113], s[18:19], 0, v[112:113]
	global_load_dwordx4 v[64:67], v[112:113], off
	global_load_dwordx4 v[68:71], v[112:113], off offset:16
	global_load_dwordx4 v[72:75], v[112:113], off offset:32
	global_load_dwordx4 v[76:79], v[112:113], off offset:48
	s_add_i32 s98, s98, 2
	s_mul_i32 s99, s98, s72
	s_add_i32 s99, s99, s2
	s_cmp_lt_u32 s99, 0xb00
	s_cselect_b32 s99, s99, s2
	s_and_b32 s100, s99, 7
	s_mul_i32 s100, s100, 0x160
	s_lshr_b32 s101, s99, 3
	s_add_i32 s100, s100, s101
	s_mul_hi_u32 s101, s100, 0x1745d18
	s_lshl_b32 s101, s101, 3
	s_and_b32 s100, s100, 7
	s_or_b32 s101, s101, s100
	s_lshl_b32 s101, s101, 8
	v_add_u32_e32 v112, s101, v114
	v_lshlrev_b32_e32 v112, 6, v112
	v_mov_b32_e32 v113, 0
	v_lshl_add_u64 v[112:113], s[18:19], 0, v[112:113]
	global_load_dwordx4 v[80:83], v[112:113], off
	global_load_dwordx4 v[84:87], v[112:113], off offset:16
	global_load_dwordx4 v[88:91], v[112:113], off offset:32
	global_load_dwordx4 v[92:95], v[112:113], off offset:48
	s_add_i32 s98, s98, 2
	s_mul_i32 s99, s98, s72
	s_add_i32 s99, s99, s2
	s_cmp_lt_u32 s99, 0xb00
	s_cselect_b32 s99, s99, s2
	s_and_b32 s100, s99, 7
	s_mul_i32 s100, s100, 0x160
	s_lshr_b32 s101, s99, 3
	s_add_i32 s100, s100, s101
	s_mul_hi_u32 s101, s100, 0x1745d18
	s_lshl_b32 s101, s101, 3
	s_and_b32 s100, s100, 7
	s_or_b32 s101, s101, s100
	s_lshl_b32 s101, s101, 8
	v_add_u32_e32 v112, s101, v114
	v_lshlrev_b32_e32 v112, 6, v112
	v_mov_b32_e32 v113, 0
	v_lshl_add_u64 v[112:113], s[18:19], 0, v[112:113]
	global_load_dwordx4 v[96:99], v[112:113], off
	global_load_dwordx4 v[100:103], v[112:113], off offset:16
	global_load_dwordx4 v[104:107], v[112:113], off offset:32
	global_load_dwordx4 v[108:111], v[112:113], off offset:48
	s_add_i32 s98, s98, 2
	v_lshlrev_b32_e32 v116, 2, v128
	v_add_u32_e32 v116, 0x20000, v116
	s_waitcnt vmcnt(20)
	v_pk_add_f32 v[118:119], v[18:19], v[22:23]
	v_pk_add_f32 v[120:121], v[16:17], v[20:21]
	v_pk_add_f32 v[122:123], v[26:27], v[30:31]
	v_pk_add_f32 v[124:125], v[24:25], v[28:29]
	v_pk_add_f32 v[118:119], v[118:119], v[122:123]
	v_pk_add_f32 v[120:121], v[120:121], v[124:125]
	v_add_f32_e32 v120, v121, v120
	v_add_f32_e32 v118, v118, v119
	v_add_f32_e32 v118, v120, v118
	v_fmamk_f32 v118, v118, 0x3a800000, v115
	v_rsq_f32_e32 v118, v118
	ds_write_b32 v116, v118
	s_waitcnt vmcnt(16)
	v_pk_add_f32 v[118:119], v[34:35], v[38:39]
	v_pk_add_f32 v[120:121], v[32:33], v[36:37]
	v_pk_add_f32 v[122:123], v[42:43], v[46:47]
	v_pk_add_f32 v[124:125], v[40:41], v[44:45]
	v_pk_add_f32 v[118:119], v[118:119], v[122:123]
	v_pk_add_f32 v[120:121], v[120:121], v[124:125]
	v_add_f32_e32 v120, v121, v120
	v_add_f32_e32 v118, v118, v119
	v_add_f32_e32 v118, v120, v118
	v_fmamk_f32 v118, v118, 0x3a800000, v115
	v_rsq_f32_e32 v118, v118
	ds_write_b32 v116, v118 offset:2048
	s_waitcnt vmcnt(12)
	v_pk_add_f32 v[118:119], v[50:51], v[54:55]
	v_pk_add_f32 v[120:121], v[48:49], v[52:53]
	v_pk_add_f32 v[122:123], v[58:59], v[62:63]
	v_pk_add_f32 v[124:125], v[56:57], v[60:61]
	v_pk_add_f32 v[118:119], v[118:119], v[122:123]
	v_pk_add_f32 v[120:121], v[120:121], v[124:125]
	v_add_f32_e32 v120, v121, v120
	v_add_f32_e32 v118, v118, v119
	v_add_f32_e32 v118, v120, v118
	v_fmamk_f32 v118, v118, 0x3a800000, v115
	v_rsq_f32_e32 v118, v118
	ds_write_b32 v116, v118 offset:4096
	s_waitcnt vmcnt(8)
	v_pk_add_f32 v[118:119], v[66:67], v[70:71]
	v_pk_add_f32 v[120:121], v[64:65], v[68:69]
	v_pk_add_f32 v[122:123], v[74:75], v[78:79]
	v_pk_add_f32 v[124:125], v[72:73], v[76:77]
	v_pk_add_f32 v[118:119], v[118:119], v[122:123]
	v_pk_add_f32 v[120:121], v[120:121], v[124:125]
	v_add_f32_e32 v120, v121, v120
	v_add_f32_e32 v118, v118, v119
	v_add_f32_e32 v118, v120, v118
	v_fmamk_f32 v118, v118, 0x3a800000, v115
	v_rsq_f32_e32 v118, v118
	ds_write_b32 v116, v118 offset:6144
	s_waitcnt vmcnt(4)
	v_pk_add_f32 v[118:119], v[82:83], v[86:87]
	v_pk_add_f32 v[120:121], v[80:81], v[84:85]
	v_pk_add_f32 v[122:123], v[90:91], v[94:95]
	v_pk_add_f32 v[124:125], v[88:89], v[92:93]
	v_pk_add_f32 v[118:119], v[118:119], v[122:123]
	v_pk_add_f32 v[120:121], v[120:121], v[124:125]
	v_add_f32_e32 v120, v121, v120
	v_add_f32_e32 v118, v118, v119
	v_add_f32_e32 v118, v120, v118
	v_fmamk_f32 v118, v118, 0x3a800000, v115
	v_rsq_f32_e32 v118, v118
	ds_write_b32 v116, v118 offset:8192
	s_waitcnt vmcnt(0)
	v_pk_add_f32 v[118:119], v[98:99], v[102:103]
	v_pk_add_f32 v[120:121], v[96:97], v[100:101]
	v_pk_add_f32 v[122:123], v[106:107], v[110:111]
	v_pk_add_f32 v[124:125], v[104:105], v[108:109]
	v_pk_add_f32 v[118:119], v[118:119], v[122:123]
	v_pk_add_f32 v[120:121], v[120:121], v[124:125]
	v_add_f32_e32 v120, v121, v120
	v_add_f32_e32 v118, v118, v119
	v_add_f32_e32 v118, v120, v118
	v_fmamk_f32 v118, v118, 0x3a800000, v115
	v_rsq_f32_e32 v118, v118
	ds_write_b32 v116, v118 offset:10240
	v_mov_b32_e32 v131, v135
	v_mov_b32_e32 v137, v135
	v_mov_b32_e32 v133, v135
	s_cmp_eq_u32 s10, 1
	s_mov_b32 s12, 0
	v_lshl_add_u64 v[6:7], s[38:39], 0, v[134:135]
	v_lshl_add_u64 v[4:5], s[38:39], 0, v[130:131]
	v_lshl_add_u64 v[0:1], s[36:37], 0, v[136:137]
	s_cselect_b64 s[0:1], -1, 0
	s_cmp_lg_u32 s10, 1
	v_lshl_add_u64 v[2:3], s[36:37], 0, v[132:133]
	s_cbranch_scc1 .LBB0_1641
	s_barrier
.LBB0_1641:
	s_lshl_b32 s6, s6, 5
	s_and_b32 s22, s6, 0x60
	s_mov_b64 s[6:7], 0x80
	s_add_i32 m0, s31, 0x18000
	v_lshl_add_u64 v[6:7], v[6:7], 0, s[6:7]
	s_lshl_b32 s11, s10, 13
	s_lshl_b32 s23, s22, 7
	s_waitcnt vmcnt(2) lgkmcnt(0)
	s_barrier
	global_load_lds_dwordx4 v[6:7], off
	v_lshl_add_u64 v[4:5], v[4:5], 0, s[6:7]
	s_add_i32 m0, s31, 0x1a000
	s_add_i32 s51, s31, 0x8000
	s_add_i32 s52, s31, 0xa000
	global_load_lds_dwordx4 v[4:5], off
	v_lshl_add_u64 v[0:1], v[0:1], 0, s[6:7]
	s_mov_b32 m0, s51
	s_add_u32 s8, s38, 0x40080
	global_load_lds_dwordx4 v[0:1], off
	v_lshl_add_u64 v[0:1], v[2:3], 0, s[6:7]
	s_mov_b32 m0, s52
	s_addc_u32 s9, s39, 0
	global_load_lds_dwordx4 v[0:1], off
	s_add_i32 m0, s31, 0x1c000
	v_lshl_add_u64 v[0:1], s[8:9], 0, v[134:135]
	global_load_lds_dwordx4 v[0:1], off
	v_lshl_add_u64 v[0:1], s[8:9], 0, v[130:131]
	s_add_i32 m0, s31, 0x1e000
	s_sext_i32_i16 s13, s4
	global_load_lds_dwordx4 v[0:1], off
	v_and_b32_e32 v0, 15, v128
	v_lshlrev_b32_e32 v1, 1, v12
	v_lshl_or_b32 v150, s10, 6, v0
	v_lshl_or_b32 v2, v0, 6, v1
	v_lshlrev_b32_e32 v0, 2, v0
	v_and_b32_e32 v3, 32, v0
	v_bitop3_b32 v2, v2, s11, v3 bitop3:0xde
	v_lshlrev_b32_e32 v3, 6, v128
	s_movk_i32 s4, 0x3c0
	s_cmpk_lt_u32 s5, 0x100
	v_and_or_b32 v1, v3, s4, v1
	s_cselect_b64 s[8:9], -1, 0
	s_lshl_b32 s4, s10, 8
	s_add_i32 s4, s4, 0
	s_add_i32 s4, s4, 0x20000
	v_and_b32_e32 v3, 32, v8
	v_add_u32_e32 v152, s4, v0
	v_lshlrev_b32_e32 v0, 8, v128
	v_bitop3_b32 v151, s23, v1, v3 bitop3:0xf6
	v_and_b32_e32 v0, 0x38000, v0
	v_lshlrev_b32_e32 v1, 11, v13
	v_or3_b32 v0, v10, v0, v1
	v_add_u32_e32 v138, v0, v11
	v_lshlrev_b32_e32 v0, 4, v9
	s_waitcnt vmcnt(6)
	v_and_b32_e32 v0, 0x78000, v0
	v_or3_b32 v0, v10, v0, v1
	s_add_i32 s53, 0, 0x10000
	s_add_i32 s54, 0, 0x14000
	v_or_b32_e32 v153, s22, v12
	v_mov_b32_e32 v139, v135
	v_add_u32_e32 v140, v0, v11
	v_mov_b32_e32 v141, v135
	v_mov_b64_e32 v[142:143], 0xb00
	v_mov_b64_e32 v[144:145], 0xaff
	v_add_u32_e32 v154, s53, v151
	v_add_u32_e32 v155, s54, v151
	v_add_u32_e32 v157, 0, v2
	s_movk_i32 s55, 0x1600
	s_mov_b32 s56, 0
	s_barrier
	s_branch .LBB0_1644

.LBB0_1818:
	v_lshrrev_b32_e32 v2, 1, v128
	v_and_b32_e32 v130, 24, v2
	v_lshrrev_b32_e32 v2, 5, v128
	v_and_b32_e32 v2, 4, v2
	v_bfe_u32 v3, v128, 2, 2
	v_lshlrev_b32_e32 v0, 4, v128
	v_and_b32_e32 v1, 32, v128
	v_bfe_u32 v11, v128, 2, 4
	v_or3_b32 v2, v2, v3, v130
	v_lshrrev_b32_e32 v3, 3, v128
	s_movk_i32 s1, 0x70
	v_bitop3_b32 v9, v0, v1, 48 bitop3:0x6c
	v_and_b32_e32 v10, 64, v128
	v_and_or_b32 v4, v3, s1, v11
	s_movk_i32 s1, 0x60
	v_add_u32_e32 v12, 0x2000, v0
	s_lshr_b32 s5, s8, 6
	s_lshr_b32 s4, s8, 8
	v_or_b32_e32 v1, v9, v10
	v_and_or_b32 v3, v3, s1, v2
	v_lshrrev_b32_e32 v0, 7, v12
	s_movk_i32 s1, 0xf0
	s_lshl_b32 s50, s5, 10
	v_lshl_or_b32 v134, v3, 11, v1
	v_and_or_b32 v3, v0, s1, v11
	s_movk_i32 s1, 0xe0
	s_add_u32 s51, s70, 0x4a80000
	v_and_or_b32 v0, v0, s1, v2
	s_addc_u32 s52, s71, 0
	s_ashr_i32 s7, s6, 31
	s_ashr_i32 s1, s0, 31
	s_lshl_b64 s[10:11], s[6:7], 19
	s_lshl_b64 s[12:13], s[0:1], 19
	s_add_u32 s44, s51, s12
	s_addc_u32 s45, s52, s13
	s_add_i32 s53, s50, 0
	s_add_i32 m0, s53, 0x10000
	v_lshl_or_b32 v138, v0, 11, v1
	global_load_lds_dwordx4 v134, s[44:45]
	s_add_i32 m0, s53, 0x12000
	s_add_u32 s12, s44, 0x40000
	global_load_lds_dwordx4 v138, s[44:45]
	s_addc_u32 s13, s45, 0
	s_add_i32 m0, s53, 0x14000
	v_lshl_or_b32 v132, v4, 11, v1
	global_load_lds_dwordx4 v134, s[12:13]
	s_add_i32 m0, s53, 0x16000
	s_add_u32 s42, s14, s10
	s_addc_u32 s43, s15, s11
	s_add_i32 s54, s53, 0x2000
	global_load_lds_dwordx4 v138, s[12:13]
	s_mov_b32 m0, s53
	s_add_u32 s10, s42, 0x40000
	v_lshl_or_b32 v136, v3, 11, v1
	global_load_lds_dwordx4 v132, s[42:43]
	s_mov_b32 m0, s54
	s_addc_u32 s11, s43, 0
	s_add_i32 s55, s53, 0x4000
	global_load_lds_dwordx4 v136, s[42:43]
	s_mov_b32 m0, s55
	s_add_i32 s56, s53, 0x6000
	global_load_lds_dwordx4 v132, s[10:11]
	s_mov_b32 m0, s56
	v_mov_b32_e32 v141, 0
	global_load_lds_dwordx4 v136, s[10:11]
	v_and_b32_e32 v114, 0xff, v128
	s_lshr_b32 s98, s91, 2
	v_mov_b32_e32 v115, 0x358637bd
	s_mul_i32 s99, s98, s72
	s_add_i32 s99, s99, s2
	s_cmp_lt_u32 s99, 0x600
	s_cselect_b32 s99, s99, s2
	s_and_b32 s100, s99, 7
	s_mul_i32 s100, s100, 0xc0
	s_lshr_b32 s101, s99, 3
	s_add_i32 s100, s100, s101
	s_mul_hi_u32 s101, s100, 0x2aaaaab
	s_lshl_b32 s101, s101, 3
	s_and_b32 s100, s100, 7
	s_or_b32 s101, s101, s100
	s_lshl_b32 s101, s101, 8
	v_add_u32_e32 v112, s101, v114
	v_lshlrev_b32_e32 v112, 6, v112
	v_mov_b32_e32 v113, 0
	v_lshl_add_u64 v[112:113], s[18:19], 0, v[112:113]
	global_load_dwordx4 v[16:19], v[112:113], off
	global_load_dwordx4 v[20:23], v[112:113], off offset:16
	global_load_dwordx4 v[24:27], v[112:113], off offset:32
	global_load_dwordx4 v[28:31], v[112:113], off offset:48
	s_add_i32 s98, s98, 2
	s_mul_i32 s99, s98, s72
	s_add_i32 s99, s99, s2
	s_cmp_lt_u32 s99, 0x600
	s_cselect_b32 s99, s99, s2
	s_and_b32 s100, s99, 7
	s_mul_i32 s100, s100, 0xc0
	s_lshr_b32 s101, s99, 3
	s_add_i32 s100, s100, s101
	s_mul_hi_u32 s101, s100, 0x2aaaaab
	s_lshl_b32 s101, s101, 3
	s_and_b32 s100, s100, 7
	s_or_b32 s101, s101, s100
	s_lshl_b32 s101, s101, 8
	v_add_u32_e32 v112, s101, v114
	v_lshlrev_b32_e32 v112, 6, v112
	v_mov_b32_e32 v113, 0
	v_lshl_add_u64 v[112:113], s[18:19], 0, v[112:113]
	global_load_dwordx4 v[32:35], v[112:113], off
	global_load_dwordx4 v[36:39], v[112:113], off offset:16
	global_load_dwordx4 v[40:43], v[112:113], off offset:32
	global_load_dwordx4 v[44:47], v[112:113], off offset:48
	s_add_i32 s98, s98, 2
	s_mul_i32 s99, s98, s72
	s_add_i32 s99, s99, s2
	s_cmp_lt_u32 s99, 0x600
	s_cselect_b32 s99, s99, s2
	s_and_b32 s100, s99, 7
	s_mul_i32 s100, s100, 0xc0
	s_lshr_b32 s101, s99, 3
	s_add_i32 s100, s100, s101
	s_mul_hi_u32 s101, s100, 0x2aaaaab
	s_lshl_b32 s101, s101, 3
	s_and_b32 s100, s100, 7
	s_or_b32 s101, s101, s100
	s_lshl_b32 s101, s101, 8
	v_add_u32_e32 v112, s101, v114
	v_lshlrev_b32_e32 v112, 6, v112
	v_mov_b32_e32 v113, 0
	v_lshl_add_u64 v[112:113], s[18:19], 0, v[112:113]
	global_load_dwordx4 v[48:51], v[112:113], off
	global_load_dwordx4 v[52:55], v[112:113], off offset:16
	global_load_dwordx4 v[56:59], v[112:113], off offset:32
	global_load_dwordx4 v[60:63], v[112:113], off offset:48
	s_add_i32 s98, s98, 2
	v_lshlrev_b32_e32 v116, 2, v128
	v_add_u32_e32 v116, 0x20000, v116
	s_waitcnt vmcnt(8)
	v_pk_add_f32 v[118:119], v[18:19], v[22:23]
	v_pk_add_f32 v[120:121], v[16:17], v[20:21]
	v_pk_add_f32 v[122:123], v[26:27], v[30:31]
	v_pk_add_f32 v[124:125], v[24:25], v[28:29]
	v_pk_add_f32 v[118:119], v[118:119], v[122:123]
	v_pk_add_f32 v[120:121], v[120:121], v[124:125]
	v_add_f32_e32 v120, v121, v120
	v_add_f32_e32 v118, v118, v119
	v_add_f32_e32 v118, v120, v118
	v_fmamk_f32 v118, v118, 0x3a800000, v115
	v_rsq_f32_e32 v118, v118
	ds_write_b32 v116, v118
	s_waitcnt vmcnt(4)
	v_pk_add_f32 v[118:119], v[34:35], v[38:39]
	v_pk_add_f32 v[120:121], v[32:33], v[36:37]
	v_pk_add_f32 v[122:123], v[42:43], v[46:47]
	v_pk_add_f32 v[124:125], v[40:41], v[44:45]
	v_pk_add_f32 v[118:119], v[118:119], v[122:123]
	v_pk_add_f32 v[120:121], v[120:121], v[124:125]
	v_add_f32_e32 v120, v121, v120
	v_add_f32_e32 v118, v118, v119
	v_add_f32_e32 v118, v120, v118
	v_fmamk_f32 v118, v118, 0x3a800000, v115
	v_rsq_f32_e32 v118, v118
	ds_write_b32 v116, v118 offset:2048
	s_waitcnt vmcnt(0)
	v_pk_add_f32 v[118:119], v[50:51], v[54:55]
	v_pk_add_f32 v[120:121], v[48:49], v[52:53]
	v_pk_add_f32 v[122:123], v[58:59], v[62:63]
	v_pk_add_f32 v[124:125], v[56:57], v[60:61]
	v_pk_add_f32 v[118:119], v[118:119], v[122:123]
	v_pk_add_f32 v[120:121], v[120:121], v[124:125]
	v_add_f32_e32 v120, v121, v120
	v_add_f32_e32 v118, v118, v119
	v_add_f32_e32 v118, v120, v118
	v_fmamk_f32 v118, v118, 0x3a800000, v115
	v_rsq_f32_e32 v118, v118
	ds_write_b32 v116, v118 offset:4096
	v_mov_b32_e32 v135, v141
	v_mov_b32_e32 v139, v141
	v_mov_b32_e32 v133, v141
	v_mov_b32_e32 v137, v141
	s_cmp_eq_u32 s4, 1
	s_mov_b32 s9, 0
	v_lshl_add_u64 v[6:7], s[44:45], 0, v[134:135]
	v_lshl_add_u64 v[4:5], s[44:45], 0, v[138:139]
	v_lshl_add_u64 v[0:1], s[42:43], 0, v[132:133]
	s_cselect_b64 s[10:11], -1, 0
	s_cmp_lg_u32 s4, 1
	v_lshl_add_u64 v[2:3], s[42:43], 0, v[136:137]
	s_cbranch_scc1 .LBB0_1820
	s_barrier
.LBB0_1820:
	s_add_u32 s22, s70, 0x13700000
	s_addc_u32 s23, s71, 0
	s_lshl_b32 s5, s5, 5
	s_mov_b64 s[26:27], 0x80
	s_and_b32 s57, s5, 0x60
	s_add_i32 m0, s53, 0x18000
	v_lshl_add_u64 v[6:7], v[6:7], 0, s[26:27]
	s_lshl_b32 s1, s4, 13
	s_lshl_b32 s5, s57, 7
	s_waitcnt vmcnt(2) lgkmcnt(0)
	s_barrier
	global_load_lds_dwordx4 v[6:7], off
	v_lshl_add_u64 v[4:5], v[4:5], 0, s[26:27]
	s_add_i32 m0, s53, 0x1a000
	s_add_i32 s58, s53, 0x8000
	s_add_i32 s59, s53, 0xa000
	global_load_lds_dwordx4 v[4:5], off
	v_lshl_add_u64 v[0:1], v[0:1], 0, s[26:27]
	s_mov_b32 m0, s58
	s_add_u32 s12, s44, 0x40080
	global_load_lds_dwordx4 v[0:1], off
	v_lshl_add_u64 v[0:1], v[2:3], 0, s[26:27]
	s_mov_b32 m0, s59
	s_addc_u32 s13, s45, 0
	global_load_lds_dwordx4 v[0:1], off
	s_add_i32 m0, s53, 0x1c000
	v_lshl_add_u64 v[0:1], s[12:13], 0, v[134:135]
	global_load_lds_dwordx4 v[0:1], off
	v_lshl_add_u64 v[0:1], s[12:13], 0, v[138:139]
	s_add_i32 m0, s53, 0x1e000
	s_cmpk_lt_u32 s8, 0x100
	global_load_lds_dwordx4 v[0:1], off
	v_and_b32_e32 v0, 15, v128
	v_lshlrev_b32_e32 v1, 1, v130
	v_lshl_or_b32 v131, s4, 6, v0
	v_lshl_or_b32 v2, v0, 6, v1
	v_lshlrev_b32_e32 v0, 2, v0
	v_and_b32_e32 v3, 32, v0
	v_bitop3_b32 v2, v2, s1, v3 bitop3:0xde
	v_lshlrev_b32_e32 v3, 6, v128
	s_movk_i32 s1, 0x3c0
	v_and_or_b32 v1, v3, s1, v1
	s_cselect_b64 s[28:29], -1, 0
	s_lshl_b32 s1, s4, 8
	s_add_i32 s1, s1, 0
	s_add_i32 s1, s1, 0x20000
	v_and_b32_e32 v3, 32, v8
	v_add_u32_e32 v155, s1, v0
	v_lshlrev_b32_e32 v0, 8, v128
	v_bitop3_b32 v154, s5, v1, v3 bitop3:0xf6
	v_and_b32_e32 v0, 0x38000, v0
	v_lshlrev_b32_e32 v1, 11, v11
	v_or3_b32 v0, v9, v0, v1
	v_add_u32_e32 v142, v0, v10
	v_lshlrev_b32_e32 v0, 4, v12
	s_waitcnt vmcnt(6)
	v_and_b32_e32 v0, 0x78000, v0
	v_or3_b32 v0, v9, v0, v1
	s_add_i32 s61, 0, 0x10000
	s_add_i32 s62, 0, 0x14000
	v_mov_b32_e32 v143, v141
	v_add_u32_e32 v144, v0, v10
	v_mov_b32_e32 v145, v141
	v_mov_b64_e32 v[146:147], 0x600
	v_mov_b64_e32 v[148:149], 0x5ff
	s_movk_i32 s60, 0xc1
	v_add_u32_e32 v157, s61, v154
	v_add_u32_e32 v158, s62, v154
	v_add_u32_e32 v159, 0, v2
	s_mov_b32 s1, 0
	s_mov_b32 s63, 0
	s_barrier
	s_branch .LBB0_1823

.LBB0_2082:
	s_or_b64 exec, exec, s[0:1]
	s_cmpk_gt_i32 s2, 0xaff
	v_readfirstlane_b32 s5, v128
	s_cbranch_scc1 .LBB0_2098
	v_lshrrev_b32_e32 v0, 5, v128
	v_lshrrev_b32_e32 v2, 1, v128
	v_and_b32_e32 v0, 4, v0
	v_bfe_u32 v1, v128, 2, 2
	v_and_b32_e32 v12, 24, v2
	v_or3_b32 v0, v0, v1, v12
	v_lshlrev_b32_e32 v1, 4, v128
	v_add_u32_e32 v9, 0x2000, v1
	v_lshrrev_b32_e32 v2, 7, v9
	s_movk_i32 s0, 0xe0
	v_and_b32_e32 v4, 32, v128
	v_and_or_b32 v3, v2, s0, v0
	v_bitop3_b32 v10, v1, v4, 48 bitop3:0x6c
	v_and_b32_e32 v11, 64, v128
	v_bfe_u32 v13, v128, 2, 4
	s_movk_i32 s0, 0xf0
	s_lshr_b32 s6, s5, 6
	v_or_b32_e32 v1, v10, v11
	v_and_or_b32 v2, v2, s0, v13
	s_lshr_b32 s10, s5, 8
	s_lshl_b32 s38, s6, 10
	v_lshl_or_b32 v132, v2, 11, v1
	v_lshrrev_b32_e32 v2, 3, v128
	s_movk_i32 s0, 0x60
	s_add_u32 s39, s70, 0x5280000
	v_and_or_b32 v0, v2, s0, v0
	s_movk_i32 s0, 0x70
	s_addc_u32 s40, s71, 0
	v_lshl_or_b32 v134, v0, 11, v1
	v_and_or_b32 v0, v2, s0, v13
	s_lshr_b32 s0, s3, 29
	s_add_i32 s0, s2, s0
	s_ashr_i32 s1, s0, 3
	s_and_b32 s0, s0, -8
	s_sub_i32 s0, s2, s0
	s_cmp_lt_i32 s0, 0
	s_movk_i32 s41, 0x161
	s_cselect_b32 s4, s41, 0x160
	s_mul_i32 s0, s0, s4
	s_add_i32 s0, s0, s1
	s_mul_hi_i32 s1, s0, 0x2e8ba2e9
	s_lshr_b32 s4, s1, 31
	s_ashr_i32 s1, s1, 5
	s_add_i32 s1, s1, s4
	s_lshl_b32 s7, s1, 3
	s_mulk_i32 s1, 0xb0
	s_sub_i32 s0, s0, s1
	s_bfe_u32 s1, s0, 0x3001c
	s_add_i32 s1, s0, s1
	s_sext_i32_i16 s4, s1
	s_and_b32 s1, s1, 0xfff8
	s_sub_i32 s0, s0, s1
	s_sext_i32_i16 s0, s0
	s_lshr_b32 s4, s4, 3
	s_add_i32 s24, s7, s0
	s_ashr_i32 s25, s24, 31
	s_bfe_i64 s[8:9], s[4:5], 0x100000
	s_lshl_b64 s[0:1], s[24:25], 19
	s_lshl_b64 s[8:9], s[8:9], 19
	s_add_u32 s28, s39, s8
	s_addc_u32 s29, s40, s9
	s_add_i32 s25, s38, 0
	s_add_i32 m0, s25, 0x10000
	v_lshl_or_b32 v130, v3, 11, v1
	global_load_lds_dwordx4 v134, s[28:29]
	s_add_i32 m0, s25, 0x12000
	s_add_u32 s8, s28, 0x40000
	global_load_lds_dwordx4 v130, s[28:29]
	s_addc_u32 s9, s29, 0
	s_add_i32 m0, s25, 0x14000
	v_lshl_or_b32 v136, v0, 11, v1
	global_load_lds_dwordx4 v134, s[8:9]
	s_add_i32 m0, s25, 0x16000
	s_add_u32 s26, s14, s0
	s_addc_u32 s27, s15, s1
	s_add_i32 s42, s25, 0x2000
	global_load_lds_dwordx4 v130, s[8:9]
	s_mov_b32 m0, s25
	s_add_u32 s0, s26, 0x40000
	global_load_lds_dwordx4 v136, s[26:27]
	s_mov_b32 m0, s42
	s_addc_u32 s1, s27, 0
	s_add_i32 s43, s25, 0x4000
	global_load_lds_dwordx4 v132, s[26:27]
	s_mov_b32 m0, s43
	s_add_i32 s44, s25, 0x6000
	global_load_lds_dwordx4 v136, s[0:1]
	s_mov_b32 m0, s44
	v_mov_b32_e32 v135, 0
	global_load_lds_dwordx4 v132, s[0:1]
	v_and_b32_e32 v114, 0xff, v128
	s_lshr_b32 s98, s91, 2
	v_mov_b32_e32 v115, 0x358637bd
	s_mul_i32 s99, s98, s72
	s_add_i32 s99, s99, s2
	s_cmp_lt_u32 s99, 0xb00
	s_cselect_b32 s99, s99, s2
	s_and_b32 s100, s99, 7
	s_mul_i32 s100, s100, 0x160
	s_lshr_b32 s101, s99, 3
	s_add_i32 s100, s100, s101
	s_mul_hi_u32 s101, s100, 0x1745d18
	s_lshl_b32 s101, s101, 3
	s_and_b32 s100, s100, 7
	s_or_b32 s101, s101, s100
	s_lshl_b32 s101, s101, 8
	v_add_u32_e32 v112, s101, v114
	v_lshlrev_b32_e32 v112, 6, v112
	v_mov_b32_e32 v113, 0
	v_lshl_add_u64 v[112:113], s[18:19], 0, v[112:113]
	global_load_dwordx4 v[16:19], v[112:113], off
	global_load_dwordx4 v[20:23], v[112:113], off offset:16
	global_load_dwordx4 v[24:27], v[112:113], off offset:32
	global_load_dwordx4 v[28:31], v[112:113], off offset:48
	s_add_i32 s98, s98, 2
	s_mul_i32 s99, s98, s72
	s_add_i32 s99, s99, s2
	s_cmp_lt_u32 s99, 0xb00
	s_cselect_b32 s99, s99, s2
	s_and_b32 s100, s99, 7
	s_mul_i32 s100, s100, 0x160
	s_lshr_b32 s101, s99, 3
	s_add_i32 s100, s100, s101
	s_mul_hi_u32 s101, s100, 0x1745d18
	s_lshl_b32 s101, s101, 3
	s_and_b32 s100, s100, 7
	s_or_b32 s101, s101, s100
	s_lshl_b32 s101, s101, 8
	v_add_u32_e32 v112, s101, v114
	v_lshlrev_b32_e32 v112, 6, v112
	v_mov_b32_e32 v113, 0
	v_lshl_add_u64 v[112:113], s[18:19], 0, v[112:113]
	global_load_dwordx4 v[32:35], v[112:113], off
	global_load_dwordx4 v[36:39], v[112:113], off offset:16
	global_load_dwordx4 v[40:43], v[112:113], off offset:32
	global_load_dwordx4 v[44:47], v[112:113], off offset:48
	s_add_i32 s98, s98, 2
	s_mul_i32 s99, s98, s72
	s_add_i32 s99, s99, s2
	s_cmp_lt_u32 s99, 0xb00
	s_cselect_b32 s99, s99, s2
	s_and_b32 s100, s99, 7
	s_mul_i32 s100, s100, 0x160
	s_lshr_b32 s101, s99, 3
	s_add_i32 s100, s100, s101
	s_mul_hi_u32 s101, s100, 0x1745d18
	s_lshl_b32 s101, s101, 3
	s_and_b32 s100, s100, 7
	s_or_b32 s101, s101, s100
	s_lshl_b32 s101, s101, 8
	v_add_u32_e32 v112, s101, v114
	v_lshlrev_b32_e32 v112, 6, v112
	v_mov_b32_e32 v113, 0
	v_lshl_add_u64 v[112:113], s[18:19], 0, v[112:113]
	global_load_dwordx4 v[48:51], v[112:113], off
	global_load_dwordx4 v[52:55], v[112:113], off offset:16
	global_load_dwordx4 v[56:59], v[112:113], off offset:32
	global_load_dwordx4 v[60:63], v[112:113], off offset:48
	s_add_i32 s98, s98, 2
	s_mul_i32 s99, s98, s72
	s_add_i32 s99, s99, s2
	s_cmp_lt_u32 s99, 0xb00
	s_cselect_b32 s99, s99, s2
	s_and_b32 s100, s99, 7
	s_mul_i32 s100, s100, 0x160
	s_lshr_b32 s101, s99, 3
	s_add_i32 s100, s100, s101
	s_mul_hi_u32 s101, s100, 0x1745d18
	s_lshl_b32 s101, s101, 3
	s_and_b32 s100, s100, 7
	s_or_b32 s101, s101, s100
	s_lshl_b32 s101, s101, 8
	v_add_u32_e32 v112, s101, v114
	v_lshlrev_b32_e32 v112, 6, v112
	v_mov_b32_e32 v113, 0
	v_lshl_add_u64 v[112:113], s[18:19], 0, v[112:113]
	global_load_dwordx4 v[64:67], v[112:113], off
	global_load_dwordx4 v[68:71], v[112:113], off offset:16
	global_load_dwordx4 v[72:75], v[112:113], off offset:32
	global_load_dwordx4 v[76:79], v[112:113], off offset:48
	s_add_i32 s98, s98, 2
	s_mul_i32 s99, s98, s72
	s_add_i32 s99, s99, s2
	s_cmp_lt_u32 s99, 0xb00
	s_cselect_b32 s99, s99, s2
	s_and_b32 s100, s99, 7
	s_mul_i32 s100, s100, 0x160
	s_lshr_b32 s101, s99, 3
	s_add_i32 s100, s100, s101
	s_mul_hi_u32 s101, s100, 0x1745d18
	s_lshl_b32 s101, s101, 3
	s_and_b32 s100, s100, 7
	s_or_b32 s101, s101, s100
	s_lshl_b32 s101, s101, 8
	v_add_u32_e32 v112, s101, v114
	v_lshlrev_b32_e32 v112, 6, v112
	v_mov_b32_e32 v113, 0
	v_lshl_add_u64 v[112:113], s[18:19], 0, v[112:113]
	global_load_dwordx4 v[80:83], v[112:113], off
	global_load_dwordx4 v[84:87], v[112:113], off offset:16
	global_load_dwordx4 v[88:91], v[112:113], off offset:32
	global_load_dwordx4 v[92:95], v[112:113], off offset:48
	s_add_i32 s98, s98, 2
	s_mul_i32 s99, s98, s72
	s_add_i32 s99, s99, s2
	s_cmp_lt_u32 s99, 0xb00
	s_cselect_b32 s99, s99, s2
	s_and_b32 s100, s99, 7
	s_mul_i32 s100, s100, 0x160
	s_lshr_b32 s101, s99, 3
	s_add_i32 s100, s100, s101
	s_mul_hi_u32 s101, s100, 0x1745d18
	s_lshl_b32 s101, s101, 3
	s_and_b32 s100, s100, 7
	s_or_b32 s101, s101, s100
	s_lshl_b32 s101, s101, 8
	v_add_u32_e32 v112, s101, v114
	v_lshlrev_b32_e32 v112, 6, v112
	v_mov_b32_e32 v113, 0
	v_lshl_add_u64 v[112:113], s[18:19], 0, v[112:113]
	global_load_dwordx4 v[96:99], v[112:113], off
	global_load_dwordx4 v[100:103], v[112:113], off offset:16
	global_load_dwordx4 v[104:107], v[112:113], off offset:32
	global_load_dwordx4 v[108:111], v[112:113], off offset:48
	s_add_i32 s98, s98, 2
	v_lshlrev_b32_e32 v116, 2, v128
	v_add_u32_e32 v116, 0x20000, v116
	s_waitcnt vmcnt(20)
	v_pk_add_f32 v[118:119], v[18:19], v[22:23]
	v_pk_add_f32 v[120:121], v[16:17], v[20:21]
	v_pk_add_f32 v[122:123], v[26:27], v[30:31]
	v_pk_add_f32 v[124:125], v[24:25], v[28:29]
	v_pk_add_f32 v[118:119], v[118:119], v[122:123]
	v_pk_add_f32 v[120:121], v[120:121], v[124:125]
	v_add_f32_e32 v120, v121, v120
	v_add_f32_e32 v118, v118, v119
	v_add_f32_e32 v118, v120, v118
	v_fmamk_f32 v118, v118, 0x3a800000, v115
	v_rsq_f32_e32 v118, v118
	ds_write_b32 v116, v118
	s_waitcnt vmcnt(16)
	v_pk_add_f32 v[118:119], v[34:35], v[38:39]
	v_pk_add_f32 v[120:121], v[32:33], v[36:37]
	v_pk_add_f32 v[122:123], v[42:43], v[46:47]
	v_pk_add_f32 v[124:125], v[40:41], v[44:45]
	v_pk_add_f32 v[118:119], v[118:119], v[122:123]
	v_pk_add_f32 v[120:121], v[120:121], v[124:125]
	v_add_f32_e32 v120, v121, v120
	v_add_f32_e32 v118, v118, v119
	v_add_f32_e32 v118, v120, v118
	v_fmamk_f32 v118, v118, 0x3a800000, v115
	v_rsq_f32_e32 v118, v118
	ds_write_b32 v116, v118 offset:2048
	s_waitcnt vmcnt(12)
	v_pk_add_f32 v[118:119], v[50:51], v[54:55]
	v_pk_add_f32 v[120:121], v[48:49], v[52:53]
	v_pk_add_f32 v[122:123], v[58:59], v[62:63]
	v_pk_add_f32 v[124:125], v[56:57], v[60:61]
	v_pk_add_f32 v[118:119], v[118:119], v[122:123]
	v_pk_add_f32 v[120:121], v[120:121], v[124:125]
	v_add_f32_e32 v120, v121, v120
	v_add_f32_e32 v118, v118, v119
	v_add_f32_e32 v118, v120, v118
	v_fmamk_f32 v118, v118, 0x3a800000, v115
	v_rsq_f32_e32 v118, v118
	ds_write_b32 v116, v118 offset:4096
	s_waitcnt vmcnt(8)
	v_pk_add_f32 v[118:119], v[66:67], v[70:71]
	v_pk_add_f32 v[120:121], v[64:65], v[68:69]
	v_pk_add_f32 v[122:123], v[74:75], v[78:79]
	v_pk_add_f32 v[124:125], v[72:73], v[76:77]
	v_pk_add_f32 v[118:119], v[118:119], v[122:123]
	v_pk_add_f32 v[120:121], v[120:121], v[124:125]
	v_add_f32_e32 v120, v121, v120
	v_add_f32_e32 v118, v118, v119
	v_add_f32_e32 v118, v120, v118
	v_fmamk_f32 v118, v118, 0x3a800000, v115
	v_rsq_f32_e32 v118, v118
	ds_write_b32 v116, v118 offset:6144
	s_waitcnt vmcnt(4)
	v_pk_add_f32 v[118:119], v[82:83], v[86:87]
	v_pk_add_f32 v[120:121], v[80:81], v[84:85]
	v_pk_add_f32 v[122:123], v[90:91], v[94:95]
	v_pk_add_f32 v[124:125], v[88:89], v[92:93]
	v_pk_add_f32 v[118:119], v[118:119], v[122:123]
	v_pk_add_f32 v[120:121], v[120:121], v[124:125]
	v_add_f32_e32 v120, v121, v120
	v_add_f32_e32 v118, v118, v119
	v_add_f32_e32 v118, v120, v118
	v_fmamk_f32 v118, v118, 0x3a800000, v115
	v_rsq_f32_e32 v118, v118
	ds_write_b32 v116, v118 offset:8192
	s_waitcnt vmcnt(0)
	v_pk_add_f32 v[118:119], v[98:99], v[102:103]
	v_pk_add_f32 v[120:121], v[96:97], v[100:101]
	v_pk_add_f32 v[122:123], v[106:107], v[110:111]
	v_pk_add_f32 v[124:125], v[104:105], v[108:109]
	v_pk_add_f32 v[118:119], v[118:119], v[122:123]
	v_pk_add_f32 v[120:121], v[120:121], v[124:125]
	v_add_f32_e32 v120, v121, v120
	v_add_f32_e32 v118, v118, v119
	v_add_f32_e32 v118, v120, v118
	v_fmamk_f32 v118, v118, 0x3a800000, v115
	v_rsq_f32_e32 v118, v118
	ds_write_b32 v116, v118 offset:10240
	v_mov_b32_e32 v131, v135
	v_mov_b32_e32 v137, v135
	v_mov_b32_e32 v133, v135
	s_cmp_eq_u32 s10, 1
	s_mov_b32 s12, 0
	v_lshl_add_u64 v[6:7], s[28:29], 0, v[134:135]
	v_lshl_add_u64 v[4:5], s[28:29], 0, v[130:131]
	v_lshl_add_u64 v[0:1], s[26:27], 0, v[136:137]
	s_cselect_b64 s[0:1], -1, 0
	s_cmp_lg_u32 s10, 1
	v_lshl_add_u64 v[2:3], s[26:27], 0, v[132:133]
	s_cbranch_scc1 .LBB0_2085
	s_barrier
.LBB0_2085:
	s_lshl_b32 s6, s6, 5
	s_and_b32 s18, s6, 0x60
	s_mov_b64 s[6:7], 0x80
	s_add_i32 m0, s25, 0x18000
	v_lshl_add_u64 v[6:7], v[6:7], 0, s[6:7]
	s_lshl_b32 s11, s10, 13
	s_lshl_b32 s19, s18, 7
	s_waitcnt vmcnt(2) lgkmcnt(0)
	s_barrier
	global_load_lds_dwordx4 v[6:7], off
	v_lshl_add_u64 v[4:5], v[4:5], 0, s[6:7]
	s_add_i32 m0, s25, 0x1a000
	s_add_i32 s45, s25, 0x8000
	s_add_i32 s46, s25, 0xa000
	global_load_lds_dwordx4 v[4:5], off
	v_lshl_add_u64 v[0:1], v[0:1], 0, s[6:7]
	s_mov_b32 m0, s45
	s_add_u32 s8, s28, 0x40080
	global_load_lds_dwordx4 v[0:1], off
	v_lshl_add_u64 v[0:1], v[2:3], 0, s[6:7]
	s_mov_b32 m0, s46
	s_addc_u32 s9, s29, 0
	global_load_lds_dwordx4 v[0:1], off
	s_add_i32 m0, s25, 0x1c000
	v_lshl_add_u64 v[0:1], s[8:9], 0, v[134:135]
	global_load_lds_dwordx4 v[0:1], off
	v_lshl_add_u64 v[0:1], s[8:9], 0, v[130:131]
	s_add_i32 m0, s25, 0x1e000
	s_sext_i32_i16 s13, s4
	global_load_lds_dwordx4 v[0:1], off
	v_and_b32_e32 v0, 15, v128
	v_lshlrev_b32_e32 v1, 1, v12
	v_lshl_or_b32 v129, s10, 6, v0
	v_lshl_or_b32 v2, v0, 6, v1
	v_lshlrev_b32_e32 v0, 2, v0
	v_and_b32_e32 v3, 32, v0
	v_bitop3_b32 v2, v2, s11, v3 bitop3:0xde
	v_lshlrev_b32_e32 v3, 6, v128
	s_movk_i32 s4, 0x3c0
	s_cmpk_lt_u32 s5, 0x100
	v_and_or_b32 v1, v3, s4, v1
	s_cselect_b64 s[8:9], -1, 0
	s_lshl_b32 s4, s10, 8
	s_add_i32 s4, s4, 0
	s_add_i32 s4, s4, 0x20000
	v_and_b32_e32 v3, 32, v8
	v_add_u32_e32 v151, s4, v0
	v_lshlrev_b32_e32 v0, 8, v128
	v_bitop3_b32 v150, s19, v1, v3 bitop3:0xf6
	v_and_b32_e32 v0, 0x38000, v0
	v_lshlrev_b32_e32 v1, 11, v13
	v_or3_b32 v0, v10, v0, v1
	v_add_u32_e32 v138, v0, v11
	v_lshlrev_b32_e32 v0, 4, v9
	s_waitcnt vmcnt(6)
	v_and_b32_e32 v0, 0x78000, v0
	v_or3_b32 v0, v10, v0, v1
	s_add_i32 s47, 0, 0x10000
	s_add_i32 s48, 0, 0x14000
	v_or_b32_e32 v152, s18, v12
	v_mov_b32_e32 v139, v135
	v_add_u32_e32 v140, v0, v11
	v_mov_b32_e32 v141, v135
	v_mov_b64_e32 v[142:143], 0xb00
	v_mov_b64_e32 v[144:145], 0xaff
	v_add_u32_e32 v153, s47, v150
	v_add_u32_e32 v154, s48, v150
	v_add_u32_e32 v155, 0, v2
	s_movk_i32 s49, 0x1600
	s_mov_b32 s50, 0
	s_barrier
	s_branch .LBB0_2088
